# accumulator zeroing removed: first K-tile of each unit runs from a peeled copy whose first MFMA per accumulator uses inline 0 as C (P2,P3,P4,P7,P8,P9)
# baseline (speedup 1.0000x reference)
;     __host__ __device__ bool next(int i, Unit& u) const { if (!b.next(i >> 1, u)) return false; u.sel = i & 1; return true; }
; #define PG8_STAGE(bufoff, gbase, voff) do { _Pragma("unroll") for (int _i = 0; _i < 2; ++_i) \
;         __builtin_amdgcn_global_load_lds((const unsigned*)((const char*)(gbase) + (voff)[_i]), (PG8_LAS unsigned*)(lds + (bufoff) + ldsw + _i * 8192), 16, 0, 0); } while (0)
; #define PG8_LDA(dst, b, h) do { _Pragma("unroll") for (int m = 0; m < 4; ++m) _Pragma("unroll") for (int k = 0; k < 2; ++k) dst[m][k] = *(const PG8_LAS bf16x8*)(lds + PG8_SA(b, h) + aoff + m * 2048 + k * 1024); } while (0)
; #define PG8_LDB(dst, b, h) do { _Pragma("unroll") for (int n = 0; n < 2; ++n) _Pragma("unroll") for (int k = 0; k < 2; ++k) dst[n][k] = *(const PG8_LAS bf16x8*)(lds + PG8_SB(b, h) + boff + n * 2048 + k * 1024); } while (0)
; #define PG8_MMA(ai, bj, At, Bt) do { __builtin_amdgcn_s_setprio(1); _Pragma("unroll") for (int m = 0; m < 4; ++m) _Pragma("unroll") for (int n = 0; n < 2; ++n) _Pragma("unroll") for (int k = 0; k < 2; ++k) \
;         acc[ai][bj][m][n] = __builtin_amdgcn_mfma_f32_16x16x32_bf16(Bt[n][k], At[m][k], acc[ai][bj][m][n], 0, 0, 0); __builtin_amdgcn_s_setprio(0); } while (0)
; #define PG8_WAIT_V(n) asm volatile("s_waitcnt vmcnt(" #n ")" ::: "memory")
; #define PG8_BAR __builtin_amdgcn_s_barrier()
; template <class Epi, class Sched, bool ALIGN_EPI = false, bool SP2 = false>
; __device__ __forceinline__ void gemm_phase(PG8_LAS unsigned char* lds, const Gemm g, const Sched& S, const Epi& E) {
;     ...
;         const bool has_next = S.next(ui + 1, nxt);
;         const char* nA = has_next ? PG8_ABASE(nxt) : cA; const char* nB = has_next ? PG8_BBASE(nxt) : cB;
;         for (int t = 0; t < nt; t += 2) {
;             const bool last = (t == nt - 2);
;             const char* a1 = cA + (size_t)(t + 1) * kstepA;
;             const char* a2 = last ? nA : cA + (size_t)(t + 2) * kstepA; const char* b2 = last ? nB : cB + (size_t)(t + 2) * kstep;
;             const char* a3 = a2 + kstepA; const char* b3 = b2 + kstep;
;             if (last && has_next) S.a_ready(nxt);
;             if constexpr (SP2) {
;             PG8_LDB(B0, 0, 0); PG8_LDB(B1, 0, 1); PG8_SCHED; PG8_LDA(At, 0, 0); PG8_STAGE(PG8_SA(1, 1), a1 + hstep, voffA);
;             PG8_WAIT_V(8); PG8_WAIT_L(0); PG8_BAR; PG8_MMA(0, 0, At, B0); PG8_MMA(0, 1, At, B1); PG8_BAR; PG8_SCHED;
.LBB0_207:
	s_ashr_i32 s15, s14, 31
	s_lshl_b64 s[16:17], s[14:15], 19
	s_add_u32 s16, s28, s16
	s_addc_u32 s17, s29, s17
	s_and_b64 s[18:19], s[0:1], exec
	s_cselect_b32 s15, s17, s23
	s_cselect_b32 s50, s16, s22
	s_ashr_i32 s13, s12, 31
	s_lshl_b64 s[18:19], s[12:13], 19
	s_add_u32 s18, s30, s18
	s_addc_u32 s19, s31, s19
	s_and_b64 s[26:27], s[0:1], exec
	s_cselect_b32 s13, s19, s25
	s_cselect_b32 s51, s18, s24
	s_add_u32 s22, s22, 0x40080
	s_addc_u32 s23, s23, 0
	s_add_u32 s52, s24, 0x100
	s_addc_u32 s53, s25, 0
	s_mov_b32 s54, -2
	ds_read_b128 v[154:157], v150
	ds_read_b128 v[158:161], v150 offset:1024
	ds_read_b128 v[162:165], v150 offset:2048
	ds_read_b128 v[166:169], v150 offset:3072
	ds_read_b128 v[170:173], v151
	ds_read_b128 v[174:177], v151 offset:1024
	ds_read_b128 v[178:181], v151 offset:2048
	ds_read_b128 v[182:185], v151 offset:3072
	s_add_u32 s24, s22, 0xfffc0080
	s_addc_u32 s25, s23, -1
	s_cmp_eq_u32 s54, 12
	s_cselect_b32 s27, s15, s25
	s_cselect_b32 s26, s50, s24
	s_cselect_b32 s25, s13, s53
	s_cselect_b32 s24, s51, s52
	v_lshl_add_u64 v[218:219], s[22:23], 0, v[140:141]
	s_add_i32 m0, s37, 0xc000
	ds_read_b128 v[186:189], v152
	ds_read_b128 v[190:193], v152 offset:1024
	ds_read_b128 v[194:197], v152 offset:2048
	ds_read_b128 v[198:201], v152 offset:3072
	ds_read_b128 v[202:205], v152 offset:4096
	ds_read_b128 v[206:209], v152 offset:5120
	ds_read_b128 v[210:213], v152 offset:6144
	ds_read_b128 v[214:217], v152 offset:7168
	global_load_lds_dwordx4 v[218:219], off
	v_lshl_add_u64 v[218:219], s[22:23], 0, v[142:143]
	s_add_i32 m0, s37, 0xe000
	s_nop 0
	global_load_lds_dwordx4 v[218:219], off
	s_waitcnt vmcnt(8)
	s_waitcnt lgkmcnt(0)
	s_barrier
	s_setprio 1
	s_waitcnt lgkmcnt(0)
	v_mfma_f32_16x16x32_bf16 v[126:129], v[154:157], v[186:189], 0
	v_mfma_f32_16x16x32_bf16 v[122:125], v[162:165], v[186:189], 0
	v_mfma_f32_16x16x32_bf16 v[110:113], v[154:157], v[194:197], 0
	v_mfma_f32_16x16x32_bf16 v[106:109], v[162:165], v[194:197], 0
	v_mfma_f32_16x16x32_bf16 v[94:97], v[154:157], v[202:205], 0
	v_mfma_f32_16x16x32_bf16 v[90:93], v[162:165], v[202:205], 0
	v_mfma_f32_16x16x32_bf16 v[78:81], v[154:157], v[210:213], 0
	v_mfma_f32_16x16x32_bf16 v[74:77], v[162:165], v[210:213], 0
	v_mfma_f32_16x16x32_bf16 v[126:129], v[158:161], v[190:193], v[126:129]
	v_mfma_f32_16x16x32_bf16 v[122:125], v[166:169], v[190:193], v[122:125]
	v_mfma_f32_16x16x32_bf16 v[110:113], v[158:161], v[198:201], v[110:113]
	v_mfma_f32_16x16x32_bf16 v[106:109], v[166:169], v[198:201], v[106:109]
	v_mfma_f32_16x16x32_bf16 v[94:97], v[158:161], v[206:209], v[94:97]
	v_mfma_f32_16x16x32_bf16 v[90:93], v[166:169], v[206:209], v[90:93]
	v_mfma_f32_16x16x32_bf16 v[78:81], v[158:161], v[214:217], v[78:81]
	v_mfma_f32_16x16x32_bf16 v[74:77], v[166:169], v[214:217], v[74:77]
	s_setprio 0
	s_setprio 1
	v_mfma_f32_16x16x32_bf16 v[118:121], v[170:173], v[186:189], 0
	v_mfma_f32_16x16x32_bf16 v[114:117], v[178:181], v[186:189], 0
	v_mfma_f32_16x16x32_bf16 v[102:105], v[170:173], v[194:197], 0
	v_mfma_f32_16x16x32_bf16 v[98:101], v[178:181], v[194:197], 0
	v_mfma_f32_16x16x32_bf16 v[86:89], v[170:173], v[202:205], 0
	v_mfma_f32_16x16x32_bf16 v[82:85], v[178:181], v[202:205], 0
	v_mfma_f32_16x16x32_bf16 v[70:73], v[170:173], v[210:213], 0
	v_mfma_f32_16x16x32_bf16 v[66:69], v[178:181], v[210:213], 0
	v_mfma_f32_16x16x32_bf16 v[118:121], v[174:177], v[190:193], v[118:121]
	v_mfma_f32_16x16x32_bf16 v[114:117], v[182:185], v[190:193], v[114:117]
	v_mfma_f32_16x16x32_bf16 v[102:105], v[174:177], v[198:201], v[102:105]
	v_mfma_f32_16x16x32_bf16 v[98:101], v[182:185], v[198:201], v[98:101]
	v_mfma_f32_16x16x32_bf16 v[86:89], v[174:177], v[206:209], v[86:89]
	v_mfma_f32_16x16x32_bf16 v[82:85], v[182:185], v[206:209], v[82:85]
	v_mfma_f32_16x16x32_bf16 v[70:73], v[174:177], v[214:217], v[70:73]
	v_mfma_f32_16x16x32_bf16 v[66:69], v[182:185], v[214:217], v[66:69]
	s_setprio 0
	s_barrier
; #define PG8_STAGE(bufoff, gbase, voff) do { _Pragma("unroll") for (int _i = 0; _i < 2; ++_i) \
;         __builtin_amdgcn_global_load_lds((const unsigned*)((const char*)(gbase) + (voff)[_i]), (PG8_LAS unsigned*)(lds + (bufoff) + ldsw + _i * 8192), 16, 0, 0); } while (0)
; #define PG8_LDA(dst, b, h) do { _Pragma("unroll") for (int m = 0; m < 4; ++m) _Pragma("unroll") for (int k = 0; k < 2; ++k) dst[m][k] = *(const PG8_LAS bf16x8*)(lds + PG8_SA(b, h) + aoff + m * 2048 + k * 1024); } while (0)
; #define PG8_MMA(ai, bj, At, Bt) do { __builtin_amdgcn_s_setprio(1); _Pragma("unroll") for (int m = 0; m < 4; ++m) _Pragma("unroll") for (int n = 0; n < 2; ++n) _Pragma("unroll") for (int k = 0; k < 2; ++k) \
;         acc[ai][bj][m][n] = __builtin_amdgcn_mfma_f32_16x16x32_bf16(Bt[n][k], At[m][k], acc[ai][bj][m][n], 0, 0, 0); __builtin_amdgcn_s_setprio(0); } while (0)
; #define PG8_WAIT_V(n) asm volatile("s_waitcnt vmcnt(" #n ")" ::: "memory")
; #define PG8_WAIT_L(n) asm volatile("s_waitcnt lgkmcnt(" #n ")" ::: "memory")
; #define PG8_BAR __builtin_amdgcn_s_barrier()
; #define PG8_SCHED __builtin_amdgcn_sched_barrier(0)
; template <class Epi, class Sched, bool ALIGN_EPI = false, bool SP2 = false>
; __device__ __forceinline__ void gemm_phase(PG8_LAS unsigned char* lds, const Gemm g, const Sched& S, const Epi& E) {
;     ...
;             PG8_LDA(At, 0, 1); PG8_STAGE(PG8_SB(0, 0), b2, voffB); PG8_STAGE(PG8_SB(0, 1), b2 + hstep, voffB); PG8_STAGE(PG8_SA(0, 0), a2, voffA);
;             PG8_WAIT_V(8); PG8_WAIT_L(0); PG8_BAR; PG8_MMA(1, 0, At, B0); PG8_MMA(1, 1, At, B1); PG8_BAR; PG8_SCHED;
	s_add_i32 s55, s47, s34
	v_lshl_add_u64 v[218:219], s[24:25], 0, v[134:135]
	s_mov_b32 m0, s55
	ds_read_b128 v[186:189], v152 offset:16384
	ds_read_b128 v[190:193], v152 offset:17408
	ds_read_b128 v[194:197], v152 offset:18432
	ds_read_b128 v[198:201], v152 offset:19456
	ds_read_b128 v[202:205], v152 offset:20480
	ds_read_b128 v[206:209], v152 offset:21504
	ds_read_b128 v[210:213], v152 offset:22528
	ds_read_b128 v[214:217], v152 offset:23552
	global_load_lds_dwordx4 v[218:219], off
	s_add_i32 m0, s55, 0x2000
	s_add_u32 s56, s24, 0x40000
	v_lshl_add_u64 v[222:223], s[24:25], 0, v[130:131]
	s_addc_u32 s57, s25, 0
	s_add_i32 s55, s48, s34
	global_load_lds_dwordx4 v[222:223], off
	v_lshl_add_u64 v[224:225], s[56:57], 0, v[134:135]
	s_mov_b32 m0, s55
	v_lshl_add_u64 v[226:227], s[26:27], 0, v[132:133]
	global_load_lds_dwordx4 v[224:225], off
	v_lshl_add_u64 v[224:225], s[56:57], 0, v[130:131]
	s_add_i32 m0, s55, 0x2000
	s_nop 0
	global_load_lds_dwordx4 v[224:225], off
	v_lshl_add_u64 v[224:225], s[26:27], 0, v[136:137]
	s_mov_b32 m0, s37
	s_nop 0
	global_load_lds_dwordx4 v[224:225], off
	s_mov_b32 m0, s38
	s_nop 0
	global_load_lds_dwordx4 v[226:227], off
	s_waitcnt vmcnt(8)
	s_waitcnt lgkmcnt(0)
	s_barrier
	s_setprio 1
	s_waitcnt lgkmcnt(0)
	v_mfma_f32_16x16x32_bf16 v[62:65], v[154:157], v[186:189], 0
	v_mfma_f32_16x16x32_bf16 v[58:61], v[162:165], v[186:189], 0
	v_mfma_f32_16x16x32_bf16 v[46:49], v[154:157], v[194:197], 0
	v_mfma_f32_16x16x32_bf16 v[42:45], v[162:165], v[194:197], 0
	v_mfma_f32_16x16x32_bf16 v[30:33], v[154:157], v[202:205], 0
	v_mfma_f32_16x16x32_bf16 v[26:29], v[162:165], v[202:205], 0
	v_mfma_f32_16x16x32_bf16 v[14:17], v[154:157], v[210:213], 0
	v_mfma_f32_16x16x32_bf16 v[10:13], v[162:165], v[210:213], 0
	v_mfma_f32_16x16x32_bf16 v[62:65], v[158:161], v[190:193], v[62:65]
	v_mfma_f32_16x16x32_bf16 v[58:61], v[166:169], v[190:193], v[58:61]
	v_mfma_f32_16x16x32_bf16 v[46:49], v[158:161], v[198:201], v[46:49]
	v_mfma_f32_16x16x32_bf16 v[42:45], v[166:169], v[198:201], v[42:45]
	v_mfma_f32_16x16x32_bf16 v[30:33], v[158:161], v[206:209], v[30:33]
	v_mfma_f32_16x16x32_bf16 v[26:29], v[166:169], v[206:209], v[26:29]
	v_mfma_f32_16x16x32_bf16 v[14:17], v[158:161], v[214:217], v[14:17]
	v_mfma_f32_16x16x32_bf16 v[10:13], v[166:169], v[214:217], v[10:13]
	s_setprio 0
	s_setprio 1
	v_mfma_f32_16x16x32_bf16 v[54:57], v[170:173], v[186:189], 0
	v_mfma_f32_16x16x32_bf16 v[50:53], v[178:181], v[186:189], 0
	v_mfma_f32_16x16x32_bf16 v[38:41], v[170:173], v[194:197], 0
	v_mfma_f32_16x16x32_bf16 v[34:37], v[178:181], v[194:197], 0
	v_mfma_f32_16x16x32_bf16 v[22:25], v[170:173], v[202:205], 0
	v_mfma_f32_16x16x32_bf16 v[18:21], v[178:181], v[202:205], 0
	v_mfma_f32_16x16x32_bf16 v[6:9], v[170:173], v[210:213], 0
	v_mfma_f32_16x16x32_bf16 v[2:5], v[178:181], v[210:213], 0
	v_mfma_f32_16x16x32_bf16 v[54:57], v[174:177], v[190:193], v[54:57]
	v_mfma_f32_16x16x32_bf16 v[50:53], v[182:185], v[190:193], v[50:53]
	v_mfma_f32_16x16x32_bf16 v[38:41], v[174:177], v[198:201], v[38:41]
	v_mfma_f32_16x16x32_bf16 v[34:37], v[182:185], v[198:201], v[34:37]
	v_mfma_f32_16x16x32_bf16 v[22:25], v[174:177], v[206:209], v[22:25]
	v_mfma_f32_16x16x32_bf16 v[18:21], v[182:185], v[206:209], v[18:21]
	v_mfma_f32_16x16x32_bf16 v[6:9], v[174:177], v[214:217], v[6:9]
	v_mfma_f32_16x16x32_bf16 v[2:5], v[182:185], v[214:217], v[2:5]
	s_setprio 0
	s_barrier
	s_branch .Lpz1_mid

; #define PG8_STAGE(bufoff, gbase, voff) do { _Pragma("unroll") for (int _i = 0; _i < 2; ++_i) \
;         __builtin_amdgcn_global_load_lds((const unsigned*)((const char*)(gbase) + (voff)[_i]), (PG8_LAS unsigned*)(lds + (bufoff) + ldsw + _i * 8192), 16, 0, 0); } while (0)
; #define PG8_LDA(dst, b, h) do { _Pragma("unroll") for (int m = 0; m < 4; ++m) _Pragma("unroll") for (int k = 0; k < 2; ++k) dst[m][k] = *(const PG8_LAS bf16x8*)(lds + PG8_SA(b, h) + aoff + m * 2048 + k * 1024); } while (0)
; #define PG8_LDB(dst, b, h) do { _Pragma("unroll") for (int n = 0; n < 2; ++n) _Pragma("unroll") for (int k = 0; k < 2; ++k) dst[n][k] = *(const PG8_LAS bf16x8*)(lds + PG8_SB(b, h) + boff + n * 2048 + k * 1024); } while (0)
; #define PG8_MMA(ai, bj, At, Bt) do { __builtin_amdgcn_s_setprio(1); _Pragma("unroll") for (int m = 0; m < 4; ++m) _Pragma("unroll") for (int n = 0; n < 2; ++n) _Pragma("unroll") for (int k = 0; k < 2; ++k) \
;         acc[ai][bj][m][n] = __builtin_amdgcn_mfma_f32_16x16x32_bf16(Bt[n][k], At[m][k], acc[ai][bj][m][n], 0, 0, 0); __builtin_amdgcn_s_setprio(0); } while (0)
; #define PG8_WAIT_V(n) asm volatile("s_waitcnt vmcnt(" #n ")" ::: "memory")
; #define PG8_WAIT_L(n) asm volatile("s_waitcnt lgkmcnt(" #n ")" ::: "memory")
; #define PG8_BAR __builtin_amdgcn_s_barrier()
; #define PG8_SCHED __builtin_amdgcn_sched_barrier(0)
; template <class Epi, class Sched, bool ALIGN_EPI = false, bool SP2 = false>
; __device__ __forceinline__ void gemm_phase(PG8_LAS unsigned char* lds, const Gemm g, const Sched& S, const Epi& E) {
;     ...
;             PG8_LDB(B0, 1, 0); PG8_LDB(B1, 1, 1); PG8_SCHED; PG8_LDA(At, 1, 0); PG8_STAGE(PG8_SA(0, 1), a2 + hstep, voffA);
;             PG8_WAIT_V(8); PG8_WAIT_L(0); PG8_BAR; PG8_MMA(0, 0, At, B0); PG8_MMA(0, 1, At, B1); PG8_BAR; PG8_SCHED;
.Lpz1_mid:
	s_add_i32 s55, 0, 0x18000
	v_add_u32_e32 v138, s55, v149
	s_add_i32 s56, 0, 0x1c000
	ds_read_b128 v[154:157], v138
	ds_read_b128 v[158:161], v138 offset:1024
	ds_read_b128 v[162:165], v138 offset:2048
	ds_read_b128 v[166:169], v138 offset:3072
	v_add_u32_e32 v138, s56, v149
	ds_read_b128 v[170:173], v138
	ds_read_b128 v[174:177], v138 offset:1024
	ds_read_b128 v[178:181], v138 offset:2048
	ds_read_b128 v[182:185], v138 offset:3072
	s_add_u32 s26, s26, 0x40000
	s_addc_u32 s27, s27, 0
	s_mov_b32 m0, s39
	v_lshl_add_u64 v[228:229], s[26:27], 0, v[136:137]
	ds_read_b128 v[186:189], v152 offset:32768
	ds_read_b128 v[190:193], v152 offset:33792
	ds_read_b128 v[194:197], v152 offset:34816
	ds_read_b128 v[198:201], v152 offset:35840
	ds_read_b128 v[202:205], v152 offset:36864
	ds_read_b128 v[206:209], v152 offset:37888
	ds_read_b128 v[210:213], v152 offset:38912
	ds_read_b128 v[214:217], v152 offset:39936
	global_load_lds_dwordx4 v[228:229], off
	v_lshl_add_u64 v[228:229], s[26:27], 0, v[132:133]
	s_mov_b32 m0, s40
	s_nop 0
	global_load_lds_dwordx4 v[228:229], off
	s_waitcnt vmcnt(8)
	s_waitcnt lgkmcnt(0)
	s_barrier
	s_setprio 1
	s_waitcnt lgkmcnt(0)
	v_mfma_f32_16x16x32_bf16 v[126:129], v[154:157], v[186:189], v[126:129]
	v_mfma_f32_16x16x32_bf16 v[122:125], v[162:165], v[186:189], v[122:125]
	v_mfma_f32_16x16x32_bf16 v[110:113], v[154:157], v[194:197], v[110:113]
	v_mfma_f32_16x16x32_bf16 v[106:109], v[162:165], v[194:197], v[106:109]
	v_mfma_f32_16x16x32_bf16 v[94:97], v[154:157], v[202:205], v[94:97]
	v_mfma_f32_16x16x32_bf16 v[90:93], v[162:165], v[202:205], v[90:93]
	v_mfma_f32_16x16x32_bf16 v[78:81], v[154:157], v[210:213], v[78:81]
	v_mfma_f32_16x16x32_bf16 v[74:77], v[162:165], v[210:213], v[74:77]
	v_mfma_f32_16x16x32_bf16 v[126:129], v[158:161], v[190:193], v[126:129]
	v_mfma_f32_16x16x32_bf16 v[122:125], v[166:169], v[190:193], v[122:125]
	v_mfma_f32_16x16x32_bf16 v[110:113], v[158:161], v[198:201], v[110:113]
	v_mfma_f32_16x16x32_bf16 v[106:109], v[166:169], v[198:201], v[106:109]
	v_mfma_f32_16x16x32_bf16 v[94:97], v[158:161], v[206:209], v[94:97]
	v_mfma_f32_16x16x32_bf16 v[90:93], v[166:169], v[206:209], v[90:93]
	v_mfma_f32_16x16x32_bf16 v[78:81], v[158:161], v[214:217], v[78:81]
	v_mfma_f32_16x16x32_bf16 v[74:77], v[166:169], v[214:217], v[74:77]
	s_setprio 0
	s_setprio 1
	v_mfma_f32_16x16x32_bf16 v[118:121], v[170:173], v[186:189], v[118:121]
	v_mfma_f32_16x16x32_bf16 v[114:117], v[178:181], v[186:189], v[114:117]
	v_mfma_f32_16x16x32_bf16 v[102:105], v[170:173], v[194:197], v[102:105]
	v_mfma_f32_16x16x32_bf16 v[98:101], v[178:181], v[194:197], v[98:101]
	v_mfma_f32_16x16x32_bf16 v[86:89], v[170:173], v[202:205], v[86:89]
	v_mfma_f32_16x16x32_bf16 v[82:85], v[178:181], v[202:205], v[82:85]
	v_mfma_f32_16x16x32_bf16 v[70:73], v[170:173], v[210:213], v[70:73]
	v_mfma_f32_16x16x32_bf16 v[66:69], v[178:181], v[210:213], v[66:69]
	v_mfma_f32_16x16x32_bf16 v[118:121], v[174:177], v[190:193], v[118:121]
	v_mfma_f32_16x16x32_bf16 v[114:117], v[182:185], v[190:193], v[114:117]
	v_mfma_f32_16x16x32_bf16 v[102:105], v[174:177], v[198:201], v[102:105]
	v_mfma_f32_16x16x32_bf16 v[98:101], v[182:185], v[198:201], v[98:101]
	v_mfma_f32_16x16x32_bf16 v[86:89], v[174:177], v[206:209], v[86:89]
	v_mfma_f32_16x16x32_bf16 v[82:85], v[182:185], v[206:209], v[82:85]
	v_mfma_f32_16x16x32_bf16 v[70:73], v[174:177], v[214:217], v[70:73]
	v_mfma_f32_16x16x32_bf16 v[66:69], v[182:185], v[214:217], v[66:69]
	s_setprio 0
	s_barrier
; #define PG8_STAGE(bufoff, gbase, voff) do { _Pragma("unroll") for (int _i = 0; _i < 2; ++_i) \
;         __builtin_amdgcn_global_load_lds((const unsigned*)((const char*)(gbase) + (voff)[_i]), (PG8_LAS unsigned*)(lds + (bufoff) + ldsw + _i * 8192), 16, 0, 0); } while (0)
; #define PG8_LDA(dst, b, h) do { _Pragma("unroll") for (int m = 0; m < 4; ++m) _Pragma("unroll") for (int k = 0; k < 2; ++k) dst[m][k] = *(const PG8_LAS bf16x8*)(lds + PG8_SA(b, h) + aoff + m * 2048 + k * 1024); } while (0)
; #define PG8_MMA(ai, bj, At, Bt) do { __builtin_amdgcn_s_setprio(1); _Pragma("unroll") for (int m = 0; m < 4; ++m) _Pragma("unroll") for (int n = 0; n < 2; ++n) _Pragma("unroll") for (int k = 0; k < 2; ++k) \
;         acc[ai][bj][m][n] = __builtin_amdgcn_mfma_f32_16x16x32_bf16(Bt[n][k], At[m][k], acc[ai][bj][m][n], 0, 0, 0); __builtin_amdgcn_s_setprio(0); } while (0)
; #define PG8_WAIT_V(n) asm volatile("s_waitcnt vmcnt(" #n ")" ::: "memory")
; #define PG8_WAIT_L(n) asm volatile("s_waitcnt lgkmcnt(" #n ")" ::: "memory")
; #define PG8_BAR __builtin_amdgcn_s_barrier()
; #define PG8_SCHED __builtin_amdgcn_sched_barrier(0)
; template <class Epi, class Sched, bool ALIGN_EPI = false, bool SP2 = false>
; __device__ __forceinline__ void gemm_phase(PG8_LAS unsigned char* lds, const Gemm g, const Sched& S, const Epi& E) {
;     ...
;         for (int t = 0; t < nt; t += 2) {
;     ...
;             PG8_LDA(At, 1, 1); PG8_STAGE(PG8_SB(1, 0), b3, voffB); PG8_STAGE(PG8_SB(1, 1), b3 + hstep, voffB); PG8_STAGE(PG8_SA(1, 0), a3, voffA);
;             PG8_WAIT_V(8); PG8_WAIT_L(0); PG8_BAR; PG8_MMA(1, 0, At, B0); PG8_MMA(1, 1, At, B1); PG8_BAR; PG8_SCHED;
	s_add_i32 s26, s55, s34
	v_lshl_add_u64 v[218:219], v[218:219], 0, s[8:9]
	s_mov_b32 m0, s26
	ds_read_b128 v[186:189], v152 offset:49152
	ds_read_b128 v[190:193], v152 offset:50176
	ds_read_b128 v[194:197], v152 offset:51200
	ds_read_b128 v[198:201], v152 offset:52224
	ds_read_b128 v[202:205], v152 offset:53248
	ds_read_b128 v[206:209], v152 offset:54272
	ds_read_b128 v[210:213], v152 offset:55296
	ds_read_b128 v[214:217], v152 offset:56320
	global_load_lds_dwordx4 v[218:219], off
	s_add_i32 m0, s26, 0x2000
	s_add_u32 s24, s24, 0x40080
	v_lshl_add_u64 v[218:219], v[222:223], 0, s[8:9]
	s_addc_u32 s25, s25, 0
	s_add_i32 s26, s56, s34
	global_load_lds_dwordx4 v[218:219], off
	v_lshl_add_u64 v[218:219], s[24:25], 0, v[134:135]
	s_mov_b32 m0, s26
	s_nop 0
	global_load_lds_dwordx4 v[218:219], off
	v_lshl_add_u64 v[218:219], s[24:25], 0, v[130:131]
	s_add_i32 m0, s26, 0x2000
	s_nop 0
	global_load_lds_dwordx4 v[218:219], off
	v_lshl_add_u64 v[218:219], v[224:225], 0, s[8:9]
	s_mov_b32 m0, s42
	s_nop 0
	global_load_lds_dwordx4 v[218:219], off
	v_lshl_add_u64 v[218:219], v[226:227], 0, s[8:9]
	s_mov_b32 m0, s43
	s_nop 0
	global_load_lds_dwordx4 v[218:219], off
	s_waitcnt vmcnt(8)
	s_waitcnt lgkmcnt(0)
	s_barrier
	s_setprio 1
	s_waitcnt lgkmcnt(0)
	v_mfma_f32_16x16x32_bf16 v[62:65], v[154:157], v[186:189], v[62:65]
	v_mfma_f32_16x16x32_bf16 v[58:61], v[162:165], v[186:189], v[58:61]
	v_mfma_f32_16x16x32_bf16 v[46:49], v[154:157], v[194:197], v[46:49]
	v_mfma_f32_16x16x32_bf16 v[42:45], v[162:165], v[194:197], v[42:45]
	v_mfma_f32_16x16x32_bf16 v[30:33], v[154:157], v[202:205], v[30:33]
	v_mfma_f32_16x16x32_bf16 v[26:29], v[162:165], v[202:205], v[26:29]
	v_mfma_f32_16x16x32_bf16 v[14:17], v[154:157], v[210:213], v[14:17]
	v_mfma_f32_16x16x32_bf16 v[10:13], v[162:165], v[210:213], v[10:13]
	v_mfma_f32_16x16x32_bf16 v[62:65], v[158:161], v[190:193], v[62:65]
	v_mfma_f32_16x16x32_bf16 v[58:61], v[166:169], v[190:193], v[58:61]
	v_mfma_f32_16x16x32_bf16 v[46:49], v[158:161], v[198:201], v[46:49]
	v_mfma_f32_16x16x32_bf16 v[42:45], v[166:169], v[198:201], v[42:45]
	v_mfma_f32_16x16x32_bf16 v[30:33], v[158:161], v[206:209], v[30:33]
	v_mfma_f32_16x16x32_bf16 v[26:29], v[166:169], v[206:209], v[26:29]
	v_mfma_f32_16x16x32_bf16 v[14:17], v[158:161], v[214:217], v[14:17]
	v_mfma_f32_16x16x32_bf16 v[10:13], v[166:169], v[214:217], v[10:13]
	s_setprio 0
	s_setprio 1
	v_mfma_f32_16x16x32_bf16 v[54:57], v[170:173], v[186:189], v[54:57]
	v_mfma_f32_16x16x32_bf16 v[50:53], v[178:181], v[186:189], v[50:53]
	v_mfma_f32_16x16x32_bf16 v[38:41], v[170:173], v[194:197], v[38:41]
	v_mfma_f32_16x16x32_bf16 v[34:37], v[178:181], v[194:197], v[34:37]
	v_mfma_f32_16x16x32_bf16 v[22:25], v[170:173], v[202:205], v[22:25]
	v_mfma_f32_16x16x32_bf16 v[18:21], v[178:181], v[202:205], v[18:21]
	v_mfma_f32_16x16x32_bf16 v[6:9], v[170:173], v[210:213], v[6:9]
	v_mfma_f32_16x16x32_bf16 v[2:5], v[178:181], v[210:213], v[2:5]
	v_mfma_f32_16x16x32_bf16 v[54:57], v[174:177], v[190:193], v[54:57]
	v_mfma_f32_16x16x32_bf16 v[50:53], v[182:185], v[190:193], v[50:53]
	v_mfma_f32_16x16x32_bf16 v[38:41], v[174:177], v[198:201], v[38:41]
	v_mfma_f32_16x16x32_bf16 v[34:37], v[182:185], v[198:201], v[34:37]
	v_mfma_f32_16x16x32_bf16 v[22:25], v[174:177], v[206:209], v[22:25]
	v_mfma_f32_16x16x32_bf16 v[18:21], v[182:185], v[206:209], v[18:21]
	v_mfma_f32_16x16x32_bf16 v[6:9], v[174:177], v[214:217], v[6:9]
	v_mfma_f32_16x16x32_bf16 v[2:5], v[182:185], v[214:217], v[2:5]
	s_setprio 0
	s_barrier
	s_add_i32 s54, s54, 2
	s_add_u32 s22, s22, 0x100
	s_addc_u32 s23, s23, 0
	s_add_u32 s52, s52, 0x100
	s_addc_u32 s53, s53, 0
	s_cmp_gt_u32 s54, 13
	s_cbranch_scc0 .LBB0_208
	s_and_b64 vcc, exec, s[10:11]
	s_cbranch_vccz .LBB0_211
	s_barrier

;     __host__ __device__ bool next(int i, Unit& u) const { if (!b.next(i >> 1, u)) return false; u.sel = i & 1; return true; }
; #define PG8_STAGE(bufoff, gbase, voff) do { _Pragma("unroll") for (int _i = 0; _i < 2; ++_i) \
;         __builtin_amdgcn_global_load_lds((const unsigned*)((const char*)(gbase) + (voff)[_i]), (PG8_LAS unsigned*)(lds + (bufoff) + ldsw + _i * 8192), 16, 0, 0); } while (0)
; #define PG8_LDA(dst, b, h) do { _Pragma("unroll") for (int m = 0; m < 4; ++m) _Pragma("unroll") for (int k = 0; k < 2; ++k) dst[m][k] = *(const PG8_LAS bf16x8*)(lds + PG8_SA(b, h) + aoff + m * 2048 + k * 1024); } while (0)
; #define PG8_LDB(dst, b, h) do { _Pragma("unroll") for (int n = 0; n < 2; ++n) _Pragma("unroll") for (int k = 0; k < 2; ++k) dst[n][k] = *(const PG8_LAS bf16x8*)(lds + PG8_SB(b, h) + boff + n * 2048 + k * 1024); } while (0)
; #define PG8_WAIT_V(n) asm volatile("s_waitcnt vmcnt(" #n ")" ::: "memory")
; #define PG8_BAR __builtin_amdgcn_s_barrier()
; template <class Epi, class Sched, bool ALIGN_EPI = false, bool SP2 = false>
; __device__ __forceinline__ void gemm_phase(PG8_LAS unsigned char* lds, const Gemm g, const Sched& S, const Epi& E) {
;     ...
;         const bool has_next = S.next(ui + 1, nxt);
;         const char* nA = has_next ? PG8_ABASE(nxt) : cA; const char* nB = has_next ? PG8_BBASE(nxt) : cB;
;         for (int t = 0; t < nt; t += 2) {
;             const bool last = (t == nt - 2);
;             const char* a1 = cA + (size_t)(t + 1) * kstepA;
;             const char* a2 = last ? nA : cA + (size_t)(t + 2) * kstepA; const char* b2 = last ? nB : cB + (size_t)(t + 2) * kstep;
;             const char* a3 = a2 + kstepA; const char* b3 = b2 + kstep;
;             if (last && has_next) S.a_ready(nxt);
;             if constexpr (SP2) {
;             PG8_LDB(B0, 0, 0); PG8_LDB(B1, 0, 1); PG8_SCHED; PG8_LDA(At, 0, 0); PG8_STAGE(PG8_SA(1, 1), a1 + hstep, voffA);
;             PG8_WAIT_V(8); PG8_WAIT_L(0); PG8_BAR; PG8_MMA(0, 0, At, B0); PG8_MMA(0, 1, At, B1); PG8_BAR; PG8_SCHED;
;             if constexpr (Epi::PREFETCH) { if (t == tpf) E.prefetch(cur, wid, lane); }
;             PG8_LDA(At, 0, 1); PG8_STAGE(PG8_SB(0, 0), b2, voffB); PG8_STAGE(PG8_SB(0, 1), b2 + hstep, voffB); PG8_STAGE(PG8_SA(0, 0), a2, voffA);
;             PG8_WAIT_V(8); PG8_WAIT_L(0); PG8_BAR; PG8_MMA(1, 0, At, B0); PG8_MMA(1, 1, At, B1); PG8_BAR; PG8_SCHED;
.LBB0_288:
	s_add_u32 s39, s6, 0x100
	s_addc_u32 s40, s7, 0
	s_mov_b32 s41, -2
	ds_read_b128 v[130:133], v223
	ds_read_b128 v[134:137], v223 offset:1024
	ds_read_b128 v[138:141], v223 offset:2048
	ds_read_b128 v[142:145], v223 offset:3072
	ds_read_b128 v[164:167], v224
	ds_read_b128 v[168:171], v224 offset:1024
	ds_read_b128 v[172:175], v224 offset:2048
	ds_read_b128 v[176:179], v224 offset:3072
	s_add_u32 s0, s4, 0x200
	s_addc_u32 s1, s5, 0
	s_cmp_eq_u32 s41, 40
	s_cselect_b32 s37, s31, s1
	s_cselect_b32 s36, s30, s0
	s_cselect_b32 s7, s35, s40
	s_cselect_b32 s6, s34, s39
	v_lshl_add_u64 v[160:161], s[4:5], 0, v[156:157]
	s_add_i32 m0, s51, 0xc000
	ds_read_b128 v[180:183], v225
	ds_read_b128 v[184:187], v225 offset:1024
	ds_read_b128 v[188:191], v225 offset:2048
	ds_read_b128 v[192:195], v225 offset:3072
	ds_read_b128 v[196:199], v225 offset:4096
	ds_read_b128 v[200:203], v225 offset:5120
	ds_read_b128 v[204:207], v225 offset:6144
	ds_read_b128 v[208:211], v225 offset:7168
	global_load_lds_dwordx4 v[160:161], off
	v_lshl_add_u64 v[160:161], s[4:5], 0, v[158:159]
	s_add_i32 m0, s51, 0xe000
	s_nop 0
	global_load_lds_dwordx4 v[160:161], off
	s_waitcnt vmcnt(8)
	s_waitcnt lgkmcnt(0)
	s_barrier
	s_setprio 1
	s_waitcnt lgkmcnt(0)
	v_mfma_f32_16x16x32_bf16 v[126:129], v[130:133], v[180:183], 0
	v_mfma_f32_16x16x32_bf16 v[122:125], v[138:141], v[180:183], 0
	v_mfma_f32_16x16x32_bf16 v[110:113], v[130:133], v[188:191], 0
	v_mfma_f32_16x16x32_bf16 v[106:109], v[138:141], v[188:191], 0
	v_mfma_f32_16x16x32_bf16 v[94:97], v[130:133], v[196:199], 0
	v_mfma_f32_16x16x32_bf16 v[90:93], v[138:141], v[196:199], 0
	v_mfma_f32_16x16x32_bf16 v[78:81], v[130:133], v[204:207], 0
	v_mfma_f32_16x16x32_bf16 v[74:77], v[138:141], v[204:207], 0
	v_mfma_f32_16x16x32_bf16 v[126:129], v[134:137], v[184:187], v[126:129]
	v_mfma_f32_16x16x32_bf16 v[122:125], v[142:145], v[184:187], v[122:125]
	v_mfma_f32_16x16x32_bf16 v[110:113], v[134:137], v[192:195], v[110:113]
	v_mfma_f32_16x16x32_bf16 v[106:109], v[142:145], v[192:195], v[106:109]
	v_mfma_f32_16x16x32_bf16 v[94:97], v[134:137], v[200:203], v[94:97]
	v_mfma_f32_16x16x32_bf16 v[90:93], v[142:145], v[200:203], v[90:93]
	v_mfma_f32_16x16x32_bf16 v[78:81], v[134:137], v[208:211], v[78:81]
	v_mfma_f32_16x16x32_bf16 v[74:77], v[142:145], v[208:211], v[74:77]
	s_setprio 0
	s_setprio 1
	v_mfma_f32_16x16x32_bf16 v[118:121], v[164:167], v[180:183], 0
	v_mfma_f32_16x16x32_bf16 v[114:117], v[172:175], v[180:183], 0
	v_mfma_f32_16x16x32_bf16 v[102:105], v[164:167], v[188:191], 0
	v_mfma_f32_16x16x32_bf16 v[98:101], v[172:175], v[188:191], 0
	v_mfma_f32_16x16x32_bf16 v[86:89], v[164:167], v[196:199], 0
	v_mfma_f32_16x16x32_bf16 v[82:85], v[172:175], v[196:199], 0
	v_mfma_f32_16x16x32_bf16 v[70:73], v[164:167], v[204:207], 0
	v_mfma_f32_16x16x32_bf16 v[66:69], v[172:175], v[204:207], 0
	v_mfma_f32_16x16x32_bf16 v[118:121], v[168:171], v[184:187], v[118:121]
	v_mfma_f32_16x16x32_bf16 v[114:117], v[176:179], v[184:187], v[114:117]
	v_mfma_f32_16x16x32_bf16 v[102:105], v[168:171], v[192:195], v[102:105]
	v_mfma_f32_16x16x32_bf16 v[98:101], v[176:179], v[192:195], v[98:101]
	v_mfma_f32_16x16x32_bf16 v[86:89], v[168:171], v[200:203], v[86:89]
	v_mfma_f32_16x16x32_bf16 v[82:85], v[176:179], v[200:203], v[82:85]
	v_mfma_f32_16x16x32_bf16 v[70:73], v[168:171], v[208:211], v[70:73]
	v_mfma_f32_16x16x32_bf16 v[66:69], v[176:179], v[208:211], v[66:69]
	s_setprio 0
	s_barrier
	s_add_i32 s4, s68, s50
	v_lshl_add_u64 v[160:161], s[6:7], 0, v[148:149]
	s_mov_b32 m0, s4
	ds_read_b128 v[180:183], v225 offset:16384
	ds_read_b128 v[184:187], v225 offset:17408
	ds_read_b128 v[188:191], v225 offset:18432
	ds_read_b128 v[192:195], v225 offset:19456
	ds_read_b128 v[196:199], v225 offset:20480
	ds_read_b128 v[200:203], v225 offset:21504
	ds_read_b128 v[204:207], v225 offset:22528
	ds_read_b128 v[208:211], v225 offset:23552
	global_load_lds_dwordx4 v[160:161], off
	s_add_i32 m0, s4, 0x2000
	s_add_u32 s4, s6, 0xb0000
	v_lshl_add_u64 v[162:163], s[6:7], 0, v[152:153]
	s_addc_u32 s5, s7, 0
	s_add_i32 s42, s69, s50
	global_load_lds_dwordx4 v[162:163], off
	v_lshl_add_u64 v[212:213], s[4:5], 0, v[148:149]
	s_mov_b32 m0, s42
	v_lshl_add_u64 v[214:215], s[36:37], 0, v[150:151]
	global_load_lds_dwordx4 v[212:213], off
	v_lshl_add_u64 v[212:213], s[4:5], 0, v[152:153]
	s_add_i32 m0, s42, 0x2000
	s_nop 0
	global_load_lds_dwordx4 v[212:213], off
	v_lshl_add_u64 v[212:213], s[36:37], 0, v[146:147]
	s_mov_b32 m0, s51
	s_nop 0
	global_load_lds_dwordx4 v[212:213], off
	s_mov_b32 m0, s52
	s_nop 0
	global_load_lds_dwordx4 v[214:215], off
	s_waitcnt vmcnt(8)
	s_waitcnt lgkmcnt(0)
	s_barrier
	s_setprio 1
	s_waitcnt lgkmcnt(0)
	v_mfma_f32_16x16x32_bf16 v[62:65], v[130:133], v[180:183], 0
	v_mfma_f32_16x16x32_bf16 v[58:61], v[138:141], v[180:183], 0
	v_mfma_f32_16x16x32_bf16 v[46:49], v[130:133], v[188:191], 0
	v_mfma_f32_16x16x32_bf16 v[42:45], v[138:141], v[188:191], 0
	v_mfma_f32_16x16x32_bf16 v[30:33], v[130:133], v[196:199], 0
	v_mfma_f32_16x16x32_bf16 v[26:29], v[138:141], v[196:199], 0
	v_mfma_f32_16x16x32_bf16 v[14:17], v[130:133], v[204:207], 0
	v_mfma_f32_16x16x32_bf16 v[10:13], v[138:141], v[204:207], 0
	v_mfma_f32_16x16x32_bf16 v[62:65], v[134:137], v[184:187], v[62:65]
	v_mfma_f32_16x16x32_bf16 v[58:61], v[142:145], v[184:187], v[58:61]
	v_mfma_f32_16x16x32_bf16 v[46:49], v[134:137], v[192:195], v[46:49]
	v_mfma_f32_16x16x32_bf16 v[42:45], v[142:145], v[192:195], v[42:45]
	v_mfma_f32_16x16x32_bf16 v[30:33], v[134:137], v[200:203], v[30:33]
	v_mfma_f32_16x16x32_bf16 v[26:29], v[142:145], v[200:203], v[26:29]
	v_mfma_f32_16x16x32_bf16 v[14:17], v[134:137], v[208:211], v[14:17]
	v_mfma_f32_16x16x32_bf16 v[10:13], v[142:145], v[208:211], v[10:13]
	s_setprio 0
	s_setprio 1
	v_mfma_f32_16x16x32_bf16 v[54:57], v[164:167], v[180:183], 0
	v_mfma_f32_16x16x32_bf16 v[50:53], v[172:175], v[180:183], 0
	v_mfma_f32_16x16x32_bf16 v[38:41], v[164:167], v[188:191], 0
	v_mfma_f32_16x16x32_bf16 v[34:37], v[172:175], v[188:191], 0
	v_mfma_f32_16x16x32_bf16 v[22:25], v[164:167], v[196:199], 0
	v_mfma_f32_16x16x32_bf16 v[18:21], v[172:175], v[196:199], 0
	v_mfma_f32_16x16x32_bf16 v[6:9], v[164:167], v[204:207], 0
	v_mfma_f32_16x16x32_bf16 v[2:5], v[172:175], v[204:207], 0
	v_mfma_f32_16x16x32_bf16 v[54:57], v[168:171], v[184:187], v[54:57]
	v_mfma_f32_16x16x32_bf16 v[50:53], v[176:179], v[184:187], v[50:53]
	v_mfma_f32_16x16x32_bf16 v[38:41], v[168:171], v[192:195], v[38:41]
	v_mfma_f32_16x16x32_bf16 v[34:37], v[176:179], v[192:195], v[34:37]
	v_mfma_f32_16x16x32_bf16 v[22:25], v[168:171], v[200:203], v[22:25]
	v_mfma_f32_16x16x32_bf16 v[18:21], v[176:179], v[200:203], v[18:21]
	v_mfma_f32_16x16x32_bf16 v[6:9], v[168:171], v[208:211], v[6:9]
	v_mfma_f32_16x16x32_bf16 v[2:5], v[176:179], v[208:211], v[2:5]
	s_setprio 0
	s_barrier
	s_branch .Lpz2_mid

; #define PG8_STAGE(bufoff, gbase, voff) do { _Pragma("unroll") for (int _i = 0; _i < 2; ++_i) \
;         __builtin_amdgcn_global_load_lds((const unsigned*)((const char*)(gbase) + (voff)[_i]), (PG8_LAS unsigned*)(lds + (bufoff) + ldsw + _i * 8192), 16, 0, 0); } while (0)
; #define PG8_LDA(dst, b, h) do { _Pragma("unroll") for (int m = 0; m < 4; ++m) _Pragma("unroll") for (int k = 0; k < 2; ++k) dst[m][k] = *(const PG8_LAS bf16x8*)(lds + PG8_SA(b, h) + aoff + m * 2048 + k * 1024); } while (0)
; #define PG8_LDB(dst, b, h) do { _Pragma("unroll") for (int n = 0; n < 2; ++n) _Pragma("unroll") for (int k = 0; k < 2; ++k) dst[n][k] = *(const PG8_LAS bf16x8*)(lds + PG8_SB(b, h) + boff + n * 2048 + k * 1024); } while (0)
; #define PG8_MMA(ai, bj, At, Bt) do { __builtin_amdgcn_s_setprio(1); _Pragma("unroll") for (int m = 0; m < 4; ++m) _Pragma("unroll") for (int n = 0; n < 2; ++n) _Pragma("unroll") for (int k = 0; k < 2; ++k) \
;         acc[ai][bj][m][n] = __builtin_amdgcn_mfma_f32_16x16x32_bf16(Bt[n][k], At[m][k], acc[ai][bj][m][n], 0, 0, 0); __builtin_amdgcn_s_setprio(0); } while (0)
; #define PG8_WAIT_V(n) asm volatile("s_waitcnt vmcnt(" #n ")" ::: "memory")
; #define PG8_WAIT_L(n) asm volatile("s_waitcnt lgkmcnt(" #n ")" ::: "memory")
; #define PG8_BAR __builtin_amdgcn_s_barrier()
; #define PG8_SCHED __builtin_amdgcn_sched_barrier(0)
; template <class Epi, class Sched, bool ALIGN_EPI = false, bool SP2 = false>
; __device__ __forceinline__ void gemm_phase(PG8_LAS unsigned char* lds, const Gemm g, const Sched& S, const Epi& E) {
;     ...
;             PG8_LDB(B0, 1, 0); PG8_LDB(B1, 1, 1); PG8_SCHED; PG8_LDA(At, 1, 0); PG8_STAGE(PG8_SA(0, 1), a2 + hstep, voffA);
;             PG8_WAIT_V(8); PG8_WAIT_L(0); PG8_BAR; PG8_MMA(0, 0, At, B0); PG8_MMA(0, 1, At, B1); PG8_BAR; PG8_SCHED;
.Lpz2_mid:
	s_add_i32 s42, 0, 0x18000
	s_add_i32 s43, 0, 0x1c000
	v_add_u32_e32 v142, s42, v222
	v_add_u32_e32 v154, s43, v222
	ds_read_b128 v[130:133], v142
	ds_read_b128 v[134:137], v142 offset:1024
	ds_read_b128 v[138:141], v142 offset:2048
	ds_read_b128 v[142:145], v142 offset:3072
	ds_read_b128 v[164:167], v154
	ds_read_b128 v[168:171], v154 offset:1024
	ds_read_b128 v[172:175], v154 offset:2048
	ds_read_b128 v[176:179], v154 offset:3072
	s_add_u32 s4, s36, 0xb0000
	s_addc_u32 s5, s37, 0
	s_mov_b32 m0, s53
	v_lshl_add_u64 v[216:217], s[4:5], 0, v[146:147]
	ds_read_b128 v[180:183], v225 offset:32768
	ds_read_b128 v[184:187], v225 offset:33792
	ds_read_b128 v[188:191], v225 offset:34816
	ds_read_b128 v[192:195], v225 offset:35840
	ds_read_b128 v[196:199], v225 offset:36864
	ds_read_b128 v[200:203], v225 offset:37888
	ds_read_b128 v[204:207], v225 offset:38912
	ds_read_b128 v[208:211], v225 offset:39936
	global_load_lds_dwordx4 v[216:217], off
	v_lshl_add_u64 v[216:217], s[4:5], 0, v[150:151]
	s_mov_b32 m0, s54
	s_nop 0
	global_load_lds_dwordx4 v[216:217], off
	s_waitcnt vmcnt(8)
	s_waitcnt lgkmcnt(0)
	s_barrier
	s_setprio 1
	s_waitcnt lgkmcnt(0)
	v_mfma_f32_16x16x32_bf16 v[126:129], v[130:133], v[180:183], v[126:129]
	v_mfma_f32_16x16x32_bf16 v[122:125], v[138:141], v[180:183], v[122:125]
	v_mfma_f32_16x16x32_bf16 v[110:113], v[130:133], v[188:191], v[110:113]
	v_mfma_f32_16x16x32_bf16 v[106:109], v[138:141], v[188:191], v[106:109]
	v_mfma_f32_16x16x32_bf16 v[94:97], v[130:133], v[196:199], v[94:97]
	v_mfma_f32_16x16x32_bf16 v[90:93], v[138:141], v[196:199], v[90:93]
	v_mfma_f32_16x16x32_bf16 v[78:81], v[130:133], v[204:207], v[78:81]
	v_mfma_f32_16x16x32_bf16 v[74:77], v[138:141], v[204:207], v[74:77]
	v_mfma_f32_16x16x32_bf16 v[126:129], v[134:137], v[184:187], v[126:129]
	v_mfma_f32_16x16x32_bf16 v[122:125], v[142:145], v[184:187], v[122:125]
	v_mfma_f32_16x16x32_bf16 v[110:113], v[134:137], v[192:195], v[110:113]
	v_mfma_f32_16x16x32_bf16 v[106:109], v[142:145], v[192:195], v[106:109]
	v_mfma_f32_16x16x32_bf16 v[94:97], v[134:137], v[200:203], v[94:97]
	v_mfma_f32_16x16x32_bf16 v[90:93], v[142:145], v[200:203], v[90:93]
	v_mfma_f32_16x16x32_bf16 v[78:81], v[134:137], v[208:211], v[78:81]
	v_mfma_f32_16x16x32_bf16 v[74:77], v[142:145], v[208:211], v[74:77]
	s_setprio 0
	s_setprio 1
	v_mfma_f32_16x16x32_bf16 v[118:121], v[164:167], v[180:183], v[118:121]
	v_mfma_f32_16x16x32_bf16 v[114:117], v[172:175], v[180:183], v[114:117]
	v_mfma_f32_16x16x32_bf16 v[102:105], v[164:167], v[188:191], v[102:105]
	v_mfma_f32_16x16x32_bf16 v[98:101], v[172:175], v[188:191], v[98:101]
	v_mfma_f32_16x16x32_bf16 v[86:89], v[164:167], v[196:199], v[86:89]
	v_mfma_f32_16x16x32_bf16 v[82:85], v[172:175], v[196:199], v[82:85]
	v_mfma_f32_16x16x32_bf16 v[70:73], v[164:167], v[204:207], v[70:73]
	v_mfma_f32_16x16x32_bf16 v[66:69], v[172:175], v[204:207], v[66:69]
	v_mfma_f32_16x16x32_bf16 v[118:121], v[168:171], v[184:187], v[118:121]
	v_mfma_f32_16x16x32_bf16 v[114:117], v[176:179], v[184:187], v[114:117]
	v_mfma_f32_16x16x32_bf16 v[102:105], v[168:171], v[192:195], v[102:105]
	v_mfma_f32_16x16x32_bf16 v[98:101], v[176:179], v[192:195], v[98:101]
	v_mfma_f32_16x16x32_bf16 v[86:89], v[168:171], v[200:203], v[86:89]
	v_mfma_f32_16x16x32_bf16 v[82:85], v[176:179], v[200:203], v[82:85]
	v_mfma_f32_16x16x32_bf16 v[70:73], v[168:171], v[208:211], v[70:73]
	v_mfma_f32_16x16x32_bf16 v[66:69], v[176:179], v[208:211], v[66:69]
	s_setprio 0
	s_barrier
; #define PG8_STAGE(bufoff, gbase, voff) do { _Pragma("unroll") for (int _i = 0; _i < 2; ++_i) \
;         __builtin_amdgcn_global_load_lds((const unsigned*)((const char*)(gbase) + (voff)[_i]), (PG8_LAS unsigned*)(lds + (bufoff) + ldsw + _i * 8192), 16, 0, 0); } while (0)
; #define PG8_LDA(dst, b, h) do { _Pragma("unroll") for (int m = 0; m < 4; ++m) _Pragma("unroll") for (int k = 0; k < 2; ++k) dst[m][k] = *(const PG8_LAS bf16x8*)(lds + PG8_SA(b, h) + aoff + m * 2048 + k * 1024); } while (0)
; #define PG8_MMA(ai, bj, At, Bt) do { __builtin_amdgcn_s_setprio(1); _Pragma("unroll") for (int m = 0; m < 4; ++m) _Pragma("unroll") for (int n = 0; n < 2; ++n) _Pragma("unroll") for (int k = 0; k < 2; ++k) \
;         acc[ai][bj][m][n] = __builtin_amdgcn_mfma_f32_16x16x32_bf16(Bt[n][k], At[m][k], acc[ai][bj][m][n], 0, 0, 0); __builtin_amdgcn_s_setprio(0); } while (0)
; #define PG8_WAIT_V(n) asm volatile("s_waitcnt vmcnt(" #n ")" ::: "memory")
; #define PG8_WAIT_L(n) asm volatile("s_waitcnt lgkmcnt(" #n ")" ::: "memory")
; #define PG8_BAR __builtin_amdgcn_s_barrier()
; #define PG8_SCHED __builtin_amdgcn_sched_barrier(0)
; template <class Epi, class Sched, bool ALIGN_EPI = false, bool SP2 = false>
; __device__ __forceinline__ void gemm_phase(PG8_LAS unsigned char* lds, const Gemm g, const Sched& S, const Epi& E) {
;     ...
;             PG8_LDA(At, 1, 1); PG8_STAGE(PG8_SB(1, 0), b3, voffB); PG8_STAGE(PG8_SB(1, 1), b3 + hstep, voffB); PG8_STAGE(PG8_SA(1, 0), a3, voffA);
;             PG8_WAIT_V(8); PG8_WAIT_L(0); PG8_BAR; PG8_MMA(1, 0, At, B0); PG8_MMA(1, 1, At, B1); PG8_BAR; PG8_SCHED;
	s_add_i32 s4, s42, s50
	v_lshl_add_u64 v[160:161], v[160:161], 0, s[22:23]
	s_mov_b32 m0, s4
	ds_read_b128 v[180:183], v225 offset:49152
	ds_read_b128 v[184:187], v225 offset:50176
	ds_read_b128 v[188:191], v225 offset:51200
	ds_read_b128 v[192:195], v225 offset:52224
	ds_read_b128 v[196:199], v225 offset:53248
	ds_read_b128 v[200:203], v225 offset:54272
	ds_read_b128 v[204:207], v225 offset:55296
	ds_read_b128 v[208:211], v225 offset:56320
	global_load_lds_dwordx4 v[160:161], off
	s_add_i32 m0, s4, 0x2000
	s_add_u32 s4, s6, 0xb0080
	v_lshl_add_u64 v[160:161], v[162:163], 0, s[22:23]
	s_addc_u32 s5, s7, 0
	s_add_i32 s6, s43, s50
	global_load_lds_dwordx4 v[160:161], off
	v_lshl_add_u64 v[160:161], s[4:5], 0, v[148:149]
	s_mov_b32 m0, s6
	s_nop 0
	global_load_lds_dwordx4 v[160:161], off
	v_lshl_add_u64 v[160:161], s[4:5], 0, v[152:153]
	s_add_i32 m0, s6, 0x2000
	s_nop 0
	global_load_lds_dwordx4 v[160:161], off
	v_lshl_add_u64 v[160:161], v[212:213], 0, s[24:25]
	s_mov_b32 m0, s63
	s_nop 0
	global_load_lds_dwordx4 v[160:161], off
	v_lshl_add_u64 v[160:161], v[214:215], 0, s[24:25]
	s_mov_b32 m0, s64
	s_nop 0
	global_load_lds_dwordx4 v[160:161], off
	s_waitcnt vmcnt(8)
	s_waitcnt lgkmcnt(0)
	s_barrier
	s_setprio 1
	s_waitcnt lgkmcnt(0)
	v_mfma_f32_16x16x32_bf16 v[62:65], v[130:133], v[180:183], v[62:65]
	v_mfma_f32_16x16x32_bf16 v[58:61], v[138:141], v[180:183], v[58:61]
	v_mfma_f32_16x16x32_bf16 v[46:49], v[130:133], v[188:191], v[46:49]
	v_mfma_f32_16x16x32_bf16 v[42:45], v[138:141], v[188:191], v[42:45]
	v_mfma_f32_16x16x32_bf16 v[30:33], v[130:133], v[196:199], v[30:33]
	v_mfma_f32_16x16x32_bf16 v[26:29], v[138:141], v[196:199], v[26:29]
	v_mfma_f32_16x16x32_bf16 v[14:17], v[130:133], v[204:207], v[14:17]
	v_mfma_f32_16x16x32_bf16 v[10:13], v[138:141], v[204:207], v[10:13]
	v_mfma_f32_16x16x32_bf16 v[62:65], v[134:137], v[184:187], v[62:65]
	v_mfma_f32_16x16x32_bf16 v[58:61], v[142:145], v[184:187], v[58:61]
	v_mfma_f32_16x16x32_bf16 v[46:49], v[134:137], v[192:195], v[46:49]
	v_mfma_f32_16x16x32_bf16 v[42:45], v[142:145], v[192:195], v[42:45]
	v_mfma_f32_16x16x32_bf16 v[30:33], v[134:137], v[200:203], v[30:33]
	v_mfma_f32_16x16x32_bf16 v[26:29], v[142:145], v[200:203], v[26:29]
	v_mfma_f32_16x16x32_bf16 v[14:17], v[134:137], v[208:211], v[14:17]
	v_mfma_f32_16x16x32_bf16 v[10:13], v[142:145], v[208:211], v[10:13]
	s_setprio 0
	s_setprio 1
	v_mfma_f32_16x16x32_bf16 v[54:57], v[164:167], v[180:183], v[54:57]
	v_mfma_f32_16x16x32_bf16 v[50:53], v[172:175], v[180:183], v[50:53]
	v_mfma_f32_16x16x32_bf16 v[38:41], v[164:167], v[188:191], v[38:41]
	v_mfma_f32_16x16x32_bf16 v[34:37], v[172:175], v[188:191], v[34:37]
	v_mfma_f32_16x16x32_bf16 v[22:25], v[164:167], v[196:199], v[22:25]
	v_mfma_f32_16x16x32_bf16 v[18:21], v[172:175], v[196:199], v[18:21]
	v_mfma_f32_16x16x32_bf16 v[6:9], v[164:167], v[204:207], v[6:9]
	v_mfma_f32_16x16x32_bf16 v[2:5], v[172:175], v[204:207], v[2:5]
	v_mfma_f32_16x16x32_bf16 v[54:57], v[168:171], v[184:187], v[54:57]
	v_mfma_f32_16x16x32_bf16 v[50:53], v[176:179], v[184:187], v[50:53]
	v_mfma_f32_16x16x32_bf16 v[38:41], v[168:171], v[192:195], v[38:41]
	v_mfma_f32_16x16x32_bf16 v[34:37], v[176:179], v[192:195], v[34:37]
	v_mfma_f32_16x16x32_bf16 v[22:25], v[168:171], v[200:203], v[22:25]
	v_mfma_f32_16x16x32_bf16 v[18:21], v[176:179], v[200:203], v[18:21]
	v_mfma_f32_16x16x32_bf16 v[6:9], v[168:171], v[208:211], v[6:9]
	v_mfma_f32_16x16x32_bf16 v[2:5], v[176:179], v[208:211], v[2:5]
	s_setprio 0
	s_barrier
	s_add_i32 s41, s41, 2
	s_add_u32 s39, s39, 0x100
	s_addc_u32 s40, s40, 0
	s_cmp_gt_u32 s41, 41
	s_mov_b64 s[4:5], s[0:1]
	s_cbranch_scc0 .LBB0_289
	s_and_b64 vcc, exec, s[26:27]
	s_cbranch_vccz .LBB0_292
	s_barrier

; #define PG8_LAS __attribute__((address_space(3)))
;     __host__ __device__ bool next(int i, Unit& u) const { if (!b.next(i >> 1, u)) return false; u.sel = i & 1; return true; }
; #define PG8_STAGE(bufoff, gbase, voff) do { _Pragma("unroll") for (int _i = 0; _i < 2; ++_i) \
;         __builtin_amdgcn_global_load_lds((const unsigned*)((const char*)(gbase) + (voff)[_i]), (PG8_LAS unsigned*)(lds + (bufoff) + ldsw + _i * 8192), 16, 0, 0); } while (0)
; #define PG8_WAIT_V(n) asm volatile("s_waitcnt vmcnt(" #n ")" ::: "memory")
; #define PG8_WAIT_L(n) asm volatile("s_waitcnt lgkmcnt(" #n ")" ::: "memory")
; template <class Epi, class Sched, bool ALIGN_EPI = false, bool SP2 = false>
; __device__ __forceinline__ void gemm_phase(PG8_LAS unsigned char* lds, const Gemm g, const Sched& S, const Epi& E) {
;     ...
;         const bool has_next = S.next(ui + 1, nxt);
;         const char* nA = has_next ? PG8_ABASE(nxt) : cA; const char* nB = has_next ? PG8_BBASE(nxt) : cB;
;         for (int t = 0; t < nt; t += 2) {
;             const bool last = (t == nt - 2);
;             const char* a1 = cA + (size_t)(t + 1) * kstepA;
;             const char* a2 = last ? nA : cA + (size_t)(t + 2) * kstepA; const char* b2 = last ? nB : cB + (size_t)(t + 2) * kstep;
;             const char* a3 = a2 + kstepA; const char* b3 = b2 + kstep;
;             if (last && has_next) S.a_ready(nxt);
;             if constexpr (SP2) {
;             PG8_LDB(B0, 0, 0); PG8_LDB(B1, 0, 1); PG8_SCHED; PG8_LDA(At, 0, 0); PG8_STAGE(PG8_SA(1, 1), a1 + hstep, voffA);
;             PG8_WAIT_V(8); PG8_WAIT_L(0); PG8_BAR; PG8_MMA(0, 0, At, B0); PG8_MMA(0, 1, At, B1); PG8_BAR; PG8_SCHED;
;             if constexpr (Epi::PREFETCH) { if (t == tpf) E.prefetch(cur, wid, lane); }
; __device__ __forceinline__ void epi_prefetch(PG8_LAS unsigned char* scr, const float* ssq, const float* bias_tile, const Unit& u, int wid, int lane) {
;     unsigned lo = (unsigned)lane * 16u; asm volatile("" : "+v"(lo));
;     const char* src = (const char*)(ssq + (size_t)u.pm * BM * 16 + wid * 512);
; #pragma unroll
;     for (int j = 0; j < 2; ++j) __builtin_amdgcn_global_load_lds((const unsigned*)(src + j * 1024 + lo), (PG8_LAS unsigned*)(scr + (wid * 2 + j) * 1024), 16, 0, 0);
;     if (wid == 0) __builtin_amdgcn_global_load_lds((const unsigned*)((const char*)bias_tile + lo), (PG8_LAS unsigned*)(scr + 16384), 16, 0, 0);
; }
.LBB0_437:
	s_ashr_i32 s47, s46, 31
	s_lshl_b64 s[8:9], s[46:47], 19
	s_add_u32 s48, s64, s8
	s_addc_u32 s49, s65, s9
	s_and_b64 s[8:9], s[2:3], exec
	s_cselect_b32 s7, s49, s11
	s_cselect_b32 s31, s48, s10
	s_ashr_i32 s45, s44, 31
	s_lshl_b64 s[8:9], s[44:45], 19
	s_add_u32 s50, s66, s8
	s_addc_u32 s51, s67, s9
	s_and_b64 s[8:9], s[2:3], exec
	s_cselect_b32 s45, s51, s57
	s_cselect_b32 s47, s50, s56
	s_ashr_i32 s5, s4, 31
	s_lshl_b32 s8, s6, 8
	s_lshl_b64 s[28:29], s[4:5], 14
	s_ashr_i32 s5, s4, 5
	s_ashr_i32 s9, s8, 31
	s_add_u32 s52, s14, s28
	s_mul_hi_i32 s54, s5, 0x6800
	s_mulk_i32 s5, 0x6800
	s_addc_u32 s53, s88, s29
	s_add_u32 s5, s77, s5
	s_addc_u32 s55, s78, s54
	s_lshl_b64 s[28:29], s[8:9], 2
	s_add_u32 s54, s5, s28
	s_addc_u32 s55, s55, s29
	s_add_u32 s5, s56, 0x100
	v_lshl_add_u64 v[196:197], s[10:11], 0, v[188:189]
	v_lshl_add_u64 v[198:199], s[10:11], 0, v[190:191]
	s_addc_u32 s9, s57, 0
	s_mov_b32 s28, 0
	s_mov_b64 s[56:57], 0
	ds_read_b128 v[162:165], v208
	ds_read_b128 v[166:169], v208 offset:1024
	ds_read_b128 v[170:173], v208 offset:2048
	ds_read_b128 v[174:177], v208 offset:3072
	ds_read_b128 v[146:149], v209
	ds_read_b128 v[150:153], v209 offset:1024
	ds_read_b128 v[154:157], v209 offset:2048
	ds_read_b128 v[158:161], v209 offset:3072
	v_lshl_add_u64 v[42:43], v[196:197], 0, s[56:57]
	s_add_i32 m0, s69, 0xc000
	ds_read_b128 v[212:215], v210
	ds_read_b128 v[216:219], v210 offset:1024
	ds_read_b128 v[222:225], v210 offset:2048
	ds_read_b128 v[226:229], v210 offset:3072
	ds_read_b128 v[230:233], v210 offset:4096
	ds_read_b128 v[234:237], v210 offset:5120
	ds_read_b128 v[238:241], v210 offset:6144
	ds_read_b128 v[242:245], v210 offset:7168
	global_load_lds_dwordx4 v[42:43], off
	v_lshl_add_u64 v[42:43], v[198:199], 0, s[56:57]
	s_add_i32 m0, s69, 0xe000
	s_nop 0
	global_load_lds_dwordx4 v[42:43], off
	s_waitcnt vmcnt(8)
	s_waitcnt lgkmcnt(0)
	s_barrier
	s_setprio 1
	s_waitcnt lgkmcnt(0)
	v_mfma_f32_16x16x32_bf16 v[42:45], v[162:165], v[212:215], 0
	v_mfma_f32_16x16x32_bf16 v[46:49], v[170:173], v[212:215], 0
	v_mfma_f32_16x16x32_bf16 v[50:53], v[162:165], v[222:225], 0
	v_mfma_f32_16x16x32_bf16 v[54:57], v[170:173], v[222:225], 0
	v_mfma_f32_16x16x32_bf16 v[110:113], v[162:165], v[230:233], 0
	v_mfma_f32_16x16x32_bf16 v[106:109], v[170:173], v[230:233], 0
	v_mfma_f32_16x16x32_bf16 v[94:97], v[162:165], v[238:241], 0
	v_mfma_f32_16x16x32_bf16 v[90:93], v[170:173], v[238:241], 0
	v_mfma_f32_16x16x32_bf16 v[42:45], v[166:169], v[216:219], v[42:45]
	v_mfma_f32_16x16x32_bf16 v[46:49], v[174:177], v[216:219], v[46:49]
	v_mfma_f32_16x16x32_bf16 v[50:53], v[166:169], v[226:229], v[50:53]
	v_mfma_f32_16x16x32_bf16 v[54:57], v[174:177], v[226:229], v[54:57]
	v_mfma_f32_16x16x32_bf16 v[110:113], v[166:169], v[234:237], v[110:113]
	v_mfma_f32_16x16x32_bf16 v[106:109], v[174:177], v[234:237], v[106:109]
	v_mfma_f32_16x16x32_bf16 v[94:97], v[166:169], v[242:245], v[94:97]
	v_mfma_f32_16x16x32_bf16 v[90:93], v[174:177], v[242:245], v[90:93]
	s_setprio 0
	s_setprio 1
	v_mfma_f32_16x16x32_bf16 v[122:125], v[146:149], v[212:215], 0
	v_mfma_f32_16x16x32_bf16 v[134:137], v[150:153], v[216:219], v[122:125]
	v_mfma_f32_16x16x32_bf16 v[122:125], v[154:157], v[212:215], 0
	v_mfma_f32_16x16x32_bf16 v[118:121], v[146:149], v[222:225], 0
	v_mfma_f32_16x16x32_bf16 v[114:117], v[154:157], v[222:225], 0
	v_mfma_f32_16x16x32_bf16 v[102:105], v[146:149], v[230:233], 0
	v_mfma_f32_16x16x32_bf16 v[98:101], v[154:157], v[230:233], 0
	v_mfma_f32_16x16x32_bf16 v[86:89], v[146:149], v[238:241], 0
	v_mfma_f32_16x16x32_bf16 v[82:85], v[154:157], v[238:241], 0
	v_mfma_f32_16x16x32_bf16 v[130:133], v[158:161], v[216:219], v[122:125]
	v_mfma_f32_16x16x32_bf16 v[118:121], v[150:153], v[226:229], v[118:121]
	v_mfma_f32_16x16x32_bf16 v[114:117], v[158:161], v[226:229], v[114:117]
	v_mfma_f32_16x16x32_bf16 v[102:105], v[150:153], v[234:237], v[102:105]
	v_mfma_f32_16x16x32_bf16 v[98:101], v[158:161], v[234:237], v[98:101]
	v_mfma_f32_16x16x32_bf16 v[86:89], v[150:153], v[242:245], v[86:89]
	v_mfma_f32_16x16x32_bf16 v[82:85], v[158:161], v[242:245], v[82:85]
	s_setprio 0
	s_barrier
	s_cmp_lg_u32 s63, s28
	s_cbranch_scc1 .Lpz3_a
	v_mov_b32_e32 v186, v207
	s_add_i32 m0, s62, 0x20000
	v_lshl_add_u64 v[122:123], s[52:53], 0, v[186:187]
	s_mov_b64 s[58:59], 0x400
	global_load_lds_dwordx4 v186, s[52:53]
	v_lshl_add_u64 v[122:123], v[122:123], 0, s[58:59]
	s_add_i32 m0, s62, 0x20400
	s_andn2_b64 vcc, exec, s[40:41]
	global_load_lds_dwordx4 v[122:123], off
	s_cbranch_vccnz .Lpz3_a
	v_lshl_add_u64 v[122:123], s[54:55], 0, v[186:187]
	s_mov_b32 m0, s30
	s_nop 0
	global_load_lds_dwordx4 v[122:123], off
	s_branch .Lpz3_a
; #define PG8_STAGE(bufoff, gbase, voff) do { _Pragma("unroll") for (int _i = 0; _i < 2; ++_i) \
;         __builtin_amdgcn_global_load_lds((const unsigned*)((const char*)(gbase) + (voff)[_i]), (PG8_LAS unsigned*)(lds + (bufoff) + ldsw + _i * 8192), 16, 0, 0); } while (0)
; #define PG8_LDA(dst, b, h) do { _Pragma("unroll") for (int m = 0; m < 4; ++m) _Pragma("unroll") for (int k = 0; k < 2; ++k) dst[m][k] = *(const PG8_LAS bf16x8*)(lds + PG8_SA(b, h) + aoff + m * 2048 + k * 1024); } while (0)
; #define PG8_MMA(ai, bj, At, Bt) do { __builtin_amdgcn_s_setprio(1); _Pragma("unroll") for (int m = 0; m < 4; ++m) _Pragma("unroll") for (int n = 0; n < 2; ++n) _Pragma("unroll") for (int k = 0; k < 2; ++k) \
;         acc[ai][bj][m][n] = __builtin_amdgcn_mfma_f32_16x16x32_bf16(Bt[n][k], At[m][k], acc[ai][bj][m][n], 0, 0, 0); __builtin_amdgcn_s_setprio(0); } while (0)
; #define PG8_WAIT_V(n) asm volatile("s_waitcnt vmcnt(" #n ")" ::: "memory")
; #define PG8_WAIT_L(n) asm volatile("s_waitcnt lgkmcnt(" #n ")" ::: "memory")
; #define PG8_BAR __builtin_amdgcn_s_barrier()
; #define PG8_SCHED __builtin_amdgcn_sched_barrier(0)
; template <class Epi, class Sched, bool ALIGN_EPI = false, bool SP2 = false>
; __device__ __forceinline__ void gemm_phase(PG8_LAS unsigned char* lds, const Gemm g, const Sched& S, const Epi& E) {
;     ...
;             PG8_LDA(At, 0, 1); PG8_STAGE(PG8_SB(0, 0), b2, voffB); PG8_STAGE(PG8_SB(0, 1), b2 + hstep, voffB); PG8_STAGE(PG8_SA(0, 0), a2, voffA);
;             PG8_WAIT_V(8); PG8_WAIT_L(0); PG8_BAR; PG8_MMA(1, 0, At, B0); PG8_MMA(1, 1, At, B1); PG8_BAR; PG8_SCHED;
.Lpz3_a:
	s_add_u32 s29, s10, s56
	s_addc_u32 s58, s11, s57
	s_add_u32 s29, s29, 0x100
	s_addc_u32 s58, s58, 0
	s_add_u32 vcc_lo, s5, s56
	s_addc_u32 s59, s9, s57
	s_cmpk_eq_i32 s56, 0x700
	s_cselect_b32 s61, s7, s58
	s_cselect_b32 s59, s45, s59
	s_cselect_b32 s58, s47, vcc_lo
	s_mov_b32 m0, s70
	s_cselect_b32 s60, s31, s29
	v_lshl_add_u64 v[204:205], s[58:59], 0, v[180:181]
	s_add_u32 vcc_lo, s58, 0x40000
	ds_read_b128 v[122:125], v210 offset:16384
	ds_read_b128 v[126:129], v210 offset:17408
	ds_read_b128 v[138:141], v210 offset:18432
	ds_read_b128 v[142:145], v210 offset:19456
	ds_read_b128 v[212:215], v210 offset:20480
	ds_read_b128 v[216:219], v210 offset:21504
	ds_read_b128 v[222:225], v210 offset:22528
	ds_read_b128 v[226:229], v210 offset:23552
	global_load_lds_dwordx4 v[204:205], off
	v_lshl_add_u64 v[246:247], s[58:59], 0, v[184:185]
	s_mov_b32 m0, s71
	s_addc_u32 vcc_hi, s59, 0
	global_load_lds_dwordx4 v[246:247], off
	v_lshl_add_u64 v[230:231], vcc, 0, v[180:181]
	s_mov_b32 m0, s72
	v_lshl_add_u64 v[248:249], s[60:61], 0, v[178:179]
	global_load_lds_dwordx4 v[230:231], off
	v_lshl_add_u64 v[230:231], vcc, 0, v[184:185]
	s_mov_b32 m0, s73
	v_lshl_add_u64 v[250:251], s[60:61], 0, v[182:183]
	global_load_lds_dwordx4 v[230:231], off
	s_mov_b32 m0, s69
	s_nop 0
	global_load_lds_dwordx4 v[248:249], off
	s_mov_b32 m0, s74
	s_nop 0
	global_load_lds_dwordx4 v[250:251], off
	s_waitcnt vmcnt(8)
	s_waitcnt lgkmcnt(0)
	s_barrier
	s_setprio 1
	s_waitcnt lgkmcnt(0)
	v_mfma_f32_16x16x32_bf16 v[78:81], v[162:165], v[122:125], 0
	v_mfma_f32_16x16x32_bf16 v[74:77], v[170:173], v[122:125], 0
	v_mfma_f32_16x16x32_bf16 v[62:65], v[162:165], v[138:141], 0
	v_mfma_f32_16x16x32_bf16 v[58:61], v[170:173], v[138:141], 0
	v_mfma_f32_16x16x32_bf16 v[30:33], v[162:165], v[212:215], 0
	v_mfma_f32_16x16x32_bf16 v[26:29], v[170:173], v[212:215], 0
	v_mfma_f32_16x16x32_bf16 v[14:17], v[162:165], v[222:225], 0
	v_mfma_f32_16x16x32_bf16 v[10:13], v[170:173], v[222:225], 0
	v_mfma_f32_16x16x32_bf16 v[78:81], v[166:169], v[126:129], v[78:81]
	v_mfma_f32_16x16x32_bf16 v[74:77], v[174:177], v[126:129], v[74:77]
	v_mfma_f32_16x16x32_bf16 v[62:65], v[166:169], v[142:145], v[62:65]
	v_mfma_f32_16x16x32_bf16 v[58:61], v[174:177], v[142:145], v[58:61]
	v_mfma_f32_16x16x32_bf16 v[30:33], v[166:169], v[216:219], v[30:33]
	v_mfma_f32_16x16x32_bf16 v[26:29], v[174:177], v[216:219], v[26:29]
	v_mfma_f32_16x16x32_bf16 v[14:17], v[166:169], v[226:229], v[14:17]
	v_mfma_f32_16x16x32_bf16 v[10:13], v[174:177], v[226:229], v[10:13]
	s_setprio 0
	s_setprio 1
	v_mfma_f32_16x16x32_bf16 v[70:73], v[146:149], v[122:125], 0
	v_mfma_f32_16x16x32_bf16 v[66:69], v[154:157], v[122:125], 0
	v_mfma_f32_16x16x32_bf16 v[38:41], v[146:149], v[138:141], 0
	v_mfma_f32_16x16x32_bf16 v[34:37], v[154:157], v[138:141], 0
	v_mfma_f32_16x16x32_bf16 v[22:25], v[146:149], v[212:215], 0
	v_mfma_f32_16x16x32_bf16 v[18:21], v[154:157], v[212:215], 0
	v_mfma_f32_16x16x32_bf16 v[6:9], v[146:149], v[222:225], 0
	v_mfma_f32_16x16x32_bf16 v[2:5], v[154:157], v[222:225], 0
	v_mfma_f32_16x16x32_bf16 v[70:73], v[150:153], v[126:129], v[70:73]
	v_mfma_f32_16x16x32_bf16 v[66:69], v[158:161], v[126:129], v[66:69]
	v_mfma_f32_16x16x32_bf16 v[38:41], v[150:153], v[142:145], v[38:41]
	v_mfma_f32_16x16x32_bf16 v[34:37], v[158:161], v[142:145], v[34:37]
	v_mfma_f32_16x16x32_bf16 v[22:25], v[150:153], v[216:219], v[22:25]
	v_mfma_f32_16x16x32_bf16 v[18:21], v[158:161], v[216:219], v[18:21]
	v_mfma_f32_16x16x32_bf16 v[6:9], v[150:153], v[226:229], v[6:9]
	v_mfma_f32_16x16x32_bf16 v[2:5], v[158:161], v[226:229], v[2:5]
	s_setprio 0
	s_barrier
	s_branch .Lpz3_mid

; #define PG8_STAGE(bufoff, gbase, voff) do { _Pragma("unroll") for (int _i = 0; _i < 2; ++_i) \
;         __builtin_amdgcn_global_load_lds((const unsigned*)((const char*)(gbase) + (voff)[_i]), (PG8_LAS unsigned*)(lds + (bufoff) + ldsw + _i * 8192), 16, 0, 0); } while (0)
; #define PG8_LDA(dst, b, h) do { _Pragma("unroll") for (int m = 0; m < 4; ++m) _Pragma("unroll") for (int k = 0; k < 2; ++k) dst[m][k] = *(const PG8_LAS bf16x8*)(lds + PG8_SA(b, h) + aoff + m * 2048 + k * 1024); } while (0)
; #define PG8_LDB(dst, b, h) do { _Pragma("unroll") for (int n = 0; n < 2; ++n) _Pragma("unroll") for (int k = 0; k < 2; ++k) dst[n][k] = *(const PG8_LAS bf16x8*)(lds + PG8_SB(b, h) + boff + n * 2048 + k * 1024); } while (0)
; #define PG8_MMA(ai, bj, At, Bt) do { __builtin_amdgcn_s_setprio(1); _Pragma("unroll") for (int m = 0; m < 4; ++m) _Pragma("unroll") for (int n = 0; n < 2; ++n) _Pragma("unroll") for (int k = 0; k < 2; ++k) \
;         acc[ai][bj][m][n] = __builtin_amdgcn_mfma_f32_16x16x32_bf16(Bt[n][k], At[m][k], acc[ai][bj][m][n], 0, 0, 0); __builtin_amdgcn_s_setprio(0); } while (0)
; #define PG8_WAIT_V(n) asm volatile("s_waitcnt vmcnt(" #n ")" ::: "memory")
; #define PG8_WAIT_L(n) asm volatile("s_waitcnt lgkmcnt(" #n ")" ::: "memory")
; #define PG8_BAR __builtin_amdgcn_s_barrier()
; #define PG8_SCHED __builtin_amdgcn_sched_barrier(0)
; template <class Epi, class Sched, bool ALIGN_EPI = false, bool SP2 = false>
; __device__ __forceinline__ void gemm_phase(PG8_LAS unsigned char* lds, const Gemm g, const Sched& S, const Epi& E) {
;     ...
;             PG8_LDB(B0, 1, 0); PG8_LDB(B1, 1, 1); PG8_SCHED; PG8_LDA(At, 1, 0); PG8_STAGE(PG8_SA(0, 1), a2 + hstep, voffA);
;             PG8_WAIT_V(8); PG8_WAIT_L(0); PG8_BAR; PG8_MMA(0, 0, At, B0); PG8_MMA(0, 1, At, B1); PG8_BAR; PG8_SCHED;
.Lpz3_mid:
	s_add_i32 s29, 0, 0x18000
	v_add_u32_e32 v122, s29, v203
	s_add_i32 vcc_lo, 0, 0x1c000
	ds_read_b128 v[146:149], v122
	ds_read_b128 v[150:153], v122 offset:1024
	ds_read_b128 v[154:157], v122 offset:2048
	ds_read_b128 v[158:161], v122 offset:3072
	v_add_u32_e32 v122, vcc_lo, v203
	ds_read_b128 v[162:165], v122
	ds_read_b128 v[166:169], v122 offset:1024
	ds_read_b128 v[170:173], v122 offset:2048
	ds_read_b128 v[174:177], v122 offset:3072
	s_add_u32 s60, s60, 0x40000
	s_addc_u32 s61, s61, 0
	s_mov_b32 m0, s75
	v_lshl_add_u64 v[122:123], s[60:61], 0, v[178:179]
	ds_read_b128 v[212:215], v210 offset:32768
	ds_read_b128 v[216:219], v210 offset:33792
	ds_read_b128 v[222:225], v210 offset:34816
	ds_read_b128 v[226:229], v210 offset:35840
	ds_read_b128 v[230:233], v210 offset:36864
	ds_read_b128 v[234:237], v210 offset:37888
	ds_read_b128 v[238:241], v210 offset:38912
	ds_read_b128 v[242:245], v210 offset:39936
	global_load_lds_dwordx4 v[122:123], off
	v_lshl_add_u64 v[122:123], s[60:61], 0, v[182:183]
	s_mov_b32 m0, s76
	s_nop 0
	global_load_lds_dwordx4 v[122:123], off
	s_waitcnt vmcnt(8)
	s_waitcnt lgkmcnt(0)
	s_barrier
	s_setprio 1
	s_waitcnt lgkmcnt(0)
	v_mfma_f32_16x16x32_bf16 v[42:45], v[146:149], v[212:215], v[42:45]
	v_mfma_f32_16x16x32_bf16 v[142:145], v[150:153], v[216:219], v[42:45]
	v_mfma_f32_16x16x32_bf16 v[42:45], v[154:157], v[212:215], v[46:49]
	v_mfma_f32_16x16x32_bf16 v[138:141], v[158:161], v[216:219], v[42:45]
	v_mfma_f32_16x16x32_bf16 v[42:45], v[146:149], v[222:225], v[50:53]
	v_mfma_f32_16x16x32_bf16 v[126:129], v[150:153], v[226:229], v[42:45]
	v_mfma_f32_16x16x32_bf16 v[42:45], v[154:157], v[222:225], v[54:57]
	v_mfma_f32_16x16x32_bf16 v[122:125], v[158:161], v[226:229], v[42:45]
	v_mfma_f32_16x16x32_bf16 v[42:45], v[146:149], v[230:233], v[110:113]
	v_mfma_f32_16x16x32_bf16 v[110:113], v[150:153], v[234:237], v[42:45]
	v_mfma_f32_16x16x32_bf16 v[42:45], v[154:157], v[230:233], v[106:109]
	v_mfma_f32_16x16x32_bf16 v[106:109], v[158:161], v[234:237], v[42:45]
	v_mfma_f32_16x16x32_bf16 v[42:45], v[146:149], v[238:241], v[94:97]
	v_mfma_f32_16x16x32_bf16 v[94:97], v[150:153], v[242:245], v[42:45]
	v_mfma_f32_16x16x32_bf16 v[42:45], v[154:157], v[238:241], v[90:93]
	v_mfma_f32_16x16x32_bf16 v[90:93], v[158:161], v[242:245], v[42:45]
	s_setprio 0
	s_setprio 1
	v_mfma_f32_16x16x32_bf16 v[42:45], v[162:165], v[212:215], v[134:137]
	v_mfma_f32_16x16x32_bf16 v[134:137], v[166:169], v[216:219], v[42:45]
	v_mfma_f32_16x16x32_bf16 v[42:45], v[170:173], v[212:215], v[130:133]
	v_mfma_f32_16x16x32_bf16 v[130:133], v[174:177], v[216:219], v[42:45]
	v_mfma_f32_16x16x32_bf16 v[42:45], v[162:165], v[222:225], v[118:121]
	v_mfma_f32_16x16x32_bf16 v[118:121], v[166:169], v[226:229], v[42:45]
	v_mfma_f32_16x16x32_bf16 v[42:45], v[170:173], v[222:225], v[114:117]
	v_mfma_f32_16x16x32_bf16 v[114:117], v[174:177], v[226:229], v[42:45]
	v_mfma_f32_16x16x32_bf16 v[42:45], v[162:165], v[230:233], v[102:105]
	v_mfma_f32_16x16x32_bf16 v[102:105], v[166:169], v[234:237], v[42:45]
	v_mfma_f32_16x16x32_bf16 v[42:45], v[170:173], v[230:233], v[98:101]
	v_mfma_f32_16x16x32_bf16 v[98:101], v[174:177], v[234:237], v[42:45]
	v_mfma_f32_16x16x32_bf16 v[42:45], v[162:165], v[238:241], v[86:89]
	v_mfma_f32_16x16x32_bf16 v[86:89], v[166:169], v[242:245], v[42:45]
	v_mfma_f32_16x16x32_bf16 v[42:45], v[170:173], v[238:241], v[82:85]
	v_mfma_f32_16x16x32_bf16 v[82:85], v[174:177], v[242:245], v[42:45]
	s_setprio 0
	s_barrier
; #define PG8_STAGE(bufoff, gbase, voff) do { _Pragma("unroll") for (int _i = 0; _i < 2; ++_i) \
;         __builtin_amdgcn_global_load_lds((const unsigned*)((const char*)(gbase) + (voff)[_i]), (PG8_LAS unsigned*)(lds + (bufoff) + ldsw + _i * 8192), 16, 0, 0); } while (0)
; #define PG8_LDA(dst, b, h) do { _Pragma("unroll") for (int m = 0; m < 4; ++m) _Pragma("unroll") for (int k = 0; k < 2; ++k) dst[m][k] = *(const PG8_LAS bf16x8*)(lds + PG8_SA(b, h) + aoff + m * 2048 + k * 1024); } while (0)
; #define PG8_MMA(ai, bj, At, Bt) do { __builtin_amdgcn_s_setprio(1); _Pragma("unroll") for (int m = 0; m < 4; ++m) _Pragma("unroll") for (int n = 0; n < 2; ++n) _Pragma("unroll") for (int k = 0; k < 2; ++k) \
;         acc[ai][bj][m][n] = __builtin_amdgcn_mfma_f32_16x16x32_bf16(Bt[n][k], At[m][k], acc[ai][bj][m][n], 0, 0, 0); __builtin_amdgcn_s_setprio(0); } while (0)
; #define PG8_WAIT_V(n) asm volatile("s_waitcnt vmcnt(" #n ")" ::: "memory")
; #define PG8_WAIT_L(n) asm volatile("s_waitcnt lgkmcnt(" #n ")" ::: "memory")
; #define PG8_BAR __builtin_amdgcn_s_barrier()
; #define PG8_SCHED __builtin_amdgcn_sched_barrier(0)
; template <class Epi, class Sched, bool ALIGN_EPI = false, bool SP2 = false>
; __device__ __forceinline__ void gemm_phase(PG8_LAS unsigned char* lds, const Gemm g, const Sched& S, const Epi& E) {
;     ...
;             PG8_LDA(At, 1, 1); PG8_STAGE(PG8_SB(1, 0), b3, voffB); PG8_STAGE(PG8_SB(1, 1), b3 + hstep, voffB); PG8_STAGE(PG8_SA(1, 0), a3, voffA);
;             PG8_WAIT_V(8); PG8_WAIT_L(0); PG8_BAR; PG8_MMA(1, 0, At, B0); PG8_MMA(1, 1, At, B1); PG8_BAR; PG8_SCHED;
	s_add_i32 s29, s29, s68
	v_lshl_add_u64 v[204:205], v[204:205], 0, s[38:39]
	s_mov_b32 m0, s29
	s_nop 1
	ds_read_b128 v[42:45], v210 offset:49152
	ds_read_b128 v[46:49], v210 offset:50176
	ds_read_b128 v[50:53], v210 offset:51200
	ds_read_b128 v[54:57], v210 offset:52224
	ds_read_b128 v[212:215], v210 offset:53248
	ds_read_b128 v[216:219], v210 offset:54272
	ds_read_b128 v[222:225], v210 offset:55296
	ds_read_b128 v[226:229], v210 offset:56320
	global_load_lds_dwordx4 v[204:205], off
	s_add_i32 m0, s29, 0x2000
	s_add_u32 s58, s58, 0x40080
	v_lshl_add_u64 v[204:205], v[246:247], 0, s[38:39]
	s_addc_u32 s59, s59, 0
	s_add_i32 s29, vcc_lo, s68
	global_load_lds_dwordx4 v[204:205], off
	v_lshl_add_u64 v[204:205], s[58:59], 0, v[180:181]
	s_mov_b32 m0, s29
	s_nop 0
	global_load_lds_dwordx4 v[204:205], off
	v_lshl_add_u64 v[204:205], s[58:59], 0, v[184:185]
	s_add_i32 m0, s29, 0x2000
	s_nop 0
	global_load_lds_dwordx4 v[204:205], off
	v_lshl_add_u64 v[204:205], v[248:249], 0, s[38:39]
	s_mov_b32 m0, s81
	s_nop 0
	global_load_lds_dwordx4 v[204:205], off
	v_lshl_add_u64 v[204:205], v[250:251], 0, s[38:39]
	s_mov_b32 m0, s82
	s_nop 0
	global_load_lds_dwordx4 v[204:205], off
	s_waitcnt vmcnt(8)
	s_waitcnt lgkmcnt(0)
	s_barrier
	s_setprio 1
	s_waitcnt lgkmcnt(0)
	v_mfma_f32_16x16x32_bf16 v[78:81], v[146:149], v[42:45], v[78:81]
	v_mfma_f32_16x16x32_bf16 v[74:77], v[154:157], v[42:45], v[74:77]
	v_mfma_f32_16x16x32_bf16 v[62:65], v[146:149], v[50:53], v[62:65]
	v_mfma_f32_16x16x32_bf16 v[58:61], v[154:157], v[50:53], v[58:61]
	v_mfma_f32_16x16x32_bf16 v[30:33], v[146:149], v[212:215], v[30:33]
	v_mfma_f32_16x16x32_bf16 v[26:29], v[154:157], v[212:215], v[26:29]
	v_mfma_f32_16x16x32_bf16 v[14:17], v[146:149], v[222:225], v[14:17]
	v_mfma_f32_16x16x32_bf16 v[10:13], v[154:157], v[222:225], v[10:13]
	v_mfma_f32_16x16x32_bf16 v[78:81], v[150:153], v[46:49], v[78:81]
	v_mfma_f32_16x16x32_bf16 v[74:77], v[158:161], v[46:49], v[74:77]
	v_mfma_f32_16x16x32_bf16 v[62:65], v[150:153], v[54:57], v[62:65]
	v_mfma_f32_16x16x32_bf16 v[58:61], v[158:161], v[54:57], v[58:61]
	v_mfma_f32_16x16x32_bf16 v[30:33], v[150:153], v[216:219], v[30:33]
	v_mfma_f32_16x16x32_bf16 v[26:29], v[158:161], v[216:219], v[26:29]
	v_mfma_f32_16x16x32_bf16 v[14:17], v[150:153], v[226:229], v[14:17]
	v_mfma_f32_16x16x32_bf16 v[10:13], v[158:161], v[226:229], v[10:13]
	s_setprio 0
	s_setprio 1
	v_mfma_f32_16x16x32_bf16 v[70:73], v[162:165], v[42:45], v[70:73]
	v_mfma_f32_16x16x32_bf16 v[42:45], v[170:173], v[42:45], v[66:69]
	v_mfma_f32_16x16x32_bf16 v[38:41], v[162:165], v[50:53], v[38:41]
	v_mfma_f32_16x16x32_bf16 v[34:37], v[170:173], v[50:53], v[34:37]
	v_mfma_f32_16x16x32_bf16 v[22:25], v[162:165], v[212:215], v[22:25]
	v_mfma_f32_16x16x32_bf16 v[18:21], v[170:173], v[212:215], v[18:21]
	v_mfma_f32_16x16x32_bf16 v[6:9], v[162:165], v[222:225], v[6:9]
	v_mfma_f32_16x16x32_bf16 v[2:5], v[170:173], v[222:225], v[2:5]
	v_mfma_f32_16x16x32_bf16 v[70:73], v[166:169], v[46:49], v[70:73]
	v_mfma_f32_16x16x32_bf16 v[66:69], v[174:177], v[46:49], v[42:45]
	v_mfma_f32_16x16x32_bf16 v[38:41], v[166:169], v[54:57], v[38:41]
	v_mfma_f32_16x16x32_bf16 v[34:37], v[174:177], v[54:57], v[34:37]
	v_mfma_f32_16x16x32_bf16 v[22:25], v[166:169], v[216:219], v[22:25]
	v_mfma_f32_16x16x32_bf16 v[18:21], v[174:177], v[216:219], v[18:21]
	v_mfma_f32_16x16x32_bf16 v[6:9], v[166:169], v[226:229], v[6:9]
	v_mfma_f32_16x16x32_bf16 v[2:5], v[174:177], v[226:229], v[2:5]
	s_setprio 0
	s_barrier
	s_add_i32 s29, s28, 2
	s_add_u32 s56, s56, 0x100
	s_addc_u32 s57, s57, 0
	s_cmp_gt_u32 s28, 13
	s_mov_b32 s28, s29
	s_cbranch_scc1 .LBB0_442

;     __host__ __device__ bool next(int i, Unit& u) const { if (!b.next(i >> 1, u)) return false; u.sel = i & 1; return true; }
; #define PG8_STAGE(bufoff, gbase, voff) do { _Pragma("unroll") for (int _i = 0; _i < 2; ++_i) \
;         __builtin_amdgcn_global_load_lds((const unsigned*)((const char*)(gbase) + (voff)[_i]), (PG8_LAS unsigned*)(lds + (bufoff) + ldsw + _i * 8192), 16, 0, 0); } while (0)
; #define PG8_LDA(dst, b, h) do { _Pragma("unroll") for (int m = 0; m < 4; ++m) _Pragma("unroll") for (int k = 0; k < 2; ++k) dst[m][k] = *(const PG8_LAS bf16x8*)(lds + PG8_SA(b, h) + aoff + m * 2048 + k * 1024); } while (0)
; #define PG8_LDB(dst, b, h) do { _Pragma("unroll") for (int n = 0; n < 2; ++n) _Pragma("unroll") for (int k = 0; k < 2; ++k) dst[n][k] = *(const PG8_LAS bf16x8*)(lds + PG8_SB(b, h) + boff + n * 2048 + k * 1024); } while (0)
; #define PG8_MMA(ai, bj, At, Bt) do { __builtin_amdgcn_s_setprio(1); _Pragma("unroll") for (int m = 0; m < 4; ++m) _Pragma("unroll") for (int n = 0; n < 2; ++n) _Pragma("unroll") for (int k = 0; k < 2; ++k) \
;         acc[ai][bj][m][n] = __builtin_amdgcn_mfma_f32_16x16x32_bf16(Bt[n][k], At[m][k], acc[ai][bj][m][n], 0, 0, 0); __builtin_amdgcn_s_setprio(0); } while (0)
; #define PG8_WAIT_V(n) asm volatile("s_waitcnt vmcnt(" #n ")" ::: "memory")
; #define PG8_BAR __builtin_amdgcn_s_barrier()
; template <class Epi, class Sched, bool ALIGN_EPI = false, bool SP2 = false>
; __device__ __forceinline__ void gemm_phase(PG8_LAS unsigned char* lds, const Gemm g, const Sched& S, const Epi& E) {
;     ...
;         const bool has_next = S.next(ui + 1, nxt);
;         const char* nA = has_next ? PG8_ABASE(nxt) : cA; const char* nB = has_next ? PG8_BBASE(nxt) : cB;
;         for (int t = 0; t < nt; t += 2) {
;             const bool last = (t == nt - 2);
;             const char* a1 = cA + (size_t)(t + 1) * kstepA;
;             const char* a2 = last ? nA : cA + (size_t)(t + 2) * kstepA; const char* b2 = last ? nB : cB + (size_t)(t + 2) * kstep;
;             const char* a3 = a2 + kstepA; const char* b3 = b2 + kstep;
;             if (last && has_next) S.a_ready(nxt);
;             if constexpr (SP2) {
;             PG8_LDB(B0, 0, 0); PG8_LDB(B1, 0, 1); PG8_SCHED; PG8_LDA(At, 0, 0); PG8_STAGE(PG8_SA(1, 1), a1 + hstep, voffA);
;             PG8_WAIT_V(8); PG8_WAIT_L(0); PG8_BAR; PG8_MMA(0, 0, At, B0); PG8_MMA(0, 1, At, B1); PG8_BAR; PG8_SCHED;
.LBB0_837:
	s_ashr_i32 s29, s28, 31
	s_lshl_b64 s[30:31], s[28:29], 19
	s_add_u32 s30, s46, s30
	s_addc_u32 s31, s47, s31
	s_and_b64 s[34:35], s[2:3], exec
	s_cselect_b32 s1, s31, s5
	s_cselect_b32 s29, s30, s4
	s_ashr_i32 s27, s26, 31
	s_lshl_b64 s[34:35], s[26:27], 19
	s_add_u32 s34, s48, s34
	s_addc_u32 s35, s49, s35
	s_and_b64 s[36:37], s[2:3], exec
	s_cselect_b32 s27, s35, s7
	s_cselect_b32 s38, s34, s6
	s_add_u32 s4, s4, 0x40080
	s_addc_u32 s5, s5, 0
	s_add_u32 s39, s6, 0x100
	s_addc_u32 s40, s7, 0
	s_mov_b32 s41, -2
	s_waitcnt lgkmcnt(0)
	ds_read_b128 v[50:53], v214
	ds_read_b128 v[54:57], v214 offset:1024
	ds_read_b128 v[66:69], v214 offset:2048
	ds_read_b128 v[70:73], v214 offset:3072
	ds_read_b128 v[146:149], v215
	ds_read_b128 v[150:153], v215 offset:1024
	ds_read_b128 v[172:175], v215 offset:2048
	ds_read_b128 v[176:179], v215 offset:3072
	s_add_u32 s6, s4, 0xfffc0080
	s_addc_u32 s7, s5, -1
	s_cmp_eq_u32 s41, 12
	s_cselect_b32 s37, s1, s7
	s_cselect_b32 s36, s29, s6
	s_cselect_b32 s7, s27, s40
	s_cselect_b32 s6, s38, s39
	v_lshl_add_u64 v[218:219], s[4:5], 0, v[164:165]
	s_add_i32 m0, s51, 0xc000
	ds_read_b128 v[180:183], v216
	ds_read_b128 v[184:187], v216 offset:1024
	ds_read_b128 v[188:191], v216 offset:2048
	ds_read_b128 v[192:195], v216 offset:3072
	ds_read_b128 v[196:199], v216 offset:4096
	ds_read_b128 v[200:203], v216 offset:5120
	ds_read_b128 v[204:207], v216 offset:6144
	ds_read_b128 v[208:211], v216 offset:7168
	global_load_lds_dwordx4 v[218:219], off
	v_lshl_add_u64 v[218:219], s[4:5], 0, v[166:167]
	s_add_i32 m0, s51, 0xe000
	s_nop 0
	global_load_lds_dwordx4 v[218:219], off
	s_waitcnt vmcnt(8)
	s_waitcnt lgkmcnt(0)
	s_barrier
	s_setprio 1
	s_waitcnt lgkmcnt(0)
	v_mfma_f32_16x16x32_bf16 v[142:145], v[50:53], v[180:183], 0
	v_mfma_f32_16x16x32_bf16 v[138:141], v[66:69], v[180:183], 0
	v_mfma_f32_16x16x32_bf16 v[126:129], v[50:53], v[188:191], 0
	v_mfma_f32_16x16x32_bf16 v[122:125], v[66:69], v[188:191], 0
	v_mfma_f32_16x16x32_bf16 v[110:113], v[50:53], v[196:199], 0
	v_mfma_f32_16x16x32_bf16 v[106:109], v[66:69], v[196:199], 0
	v_mfma_f32_16x16x32_bf16 v[94:97], v[50:53], v[204:207], 0
	v_mfma_f32_16x16x32_bf16 v[90:93], v[66:69], v[204:207], 0
	v_mfma_f32_16x16x32_bf16 v[142:145], v[54:57], v[184:187], v[142:145]
	v_mfma_f32_16x16x32_bf16 v[138:141], v[70:73], v[184:187], v[138:141]
	v_mfma_f32_16x16x32_bf16 v[126:129], v[54:57], v[192:195], v[126:129]
	v_mfma_f32_16x16x32_bf16 v[122:125], v[70:73], v[192:195], v[122:125]
	v_mfma_f32_16x16x32_bf16 v[110:113], v[54:57], v[200:203], v[110:113]
	v_mfma_f32_16x16x32_bf16 v[106:109], v[70:73], v[200:203], v[106:109]
	v_mfma_f32_16x16x32_bf16 v[94:97], v[54:57], v[208:211], v[94:97]
	v_mfma_f32_16x16x32_bf16 v[90:93], v[70:73], v[208:211], v[90:93]
	s_setprio 0
	s_setprio 1
	v_mfma_f32_16x16x32_bf16 v[134:137], v[146:149], v[180:183], 0
	v_mfma_f32_16x16x32_bf16 v[130:133], v[172:175], v[180:183], 0
	v_mfma_f32_16x16x32_bf16 v[118:121], v[146:149], v[188:191], 0
	v_mfma_f32_16x16x32_bf16 v[114:117], v[172:175], v[188:191], 0
	v_mfma_f32_16x16x32_bf16 v[102:105], v[146:149], v[196:199], 0
	v_mfma_f32_16x16x32_bf16 v[98:101], v[172:175], v[196:199], 0
	v_mfma_f32_16x16x32_bf16 v[86:89], v[146:149], v[204:207], 0
	v_mfma_f32_16x16x32_bf16 v[82:85], v[172:175], v[204:207], 0
	v_mfma_f32_16x16x32_bf16 v[134:137], v[150:153], v[184:187], v[134:137]
	v_mfma_f32_16x16x32_bf16 v[130:133], v[176:179], v[184:187], v[130:133]
	v_mfma_f32_16x16x32_bf16 v[118:121], v[150:153], v[192:195], v[118:121]
	v_mfma_f32_16x16x32_bf16 v[114:117], v[176:179], v[192:195], v[114:117]
	v_mfma_f32_16x16x32_bf16 v[102:105], v[150:153], v[200:203], v[102:105]
	v_mfma_f32_16x16x32_bf16 v[98:101], v[176:179], v[200:203], v[98:101]
	v_mfma_f32_16x16x32_bf16 v[86:89], v[150:153], v[208:211], v[86:89]
	v_mfma_f32_16x16x32_bf16 v[82:85], v[176:179], v[208:211], v[82:85]
	s_setprio 0
	s_barrier
; #define PG8_STAGE(bufoff, gbase, voff) do { _Pragma("unroll") for (int _i = 0; _i < 2; ++_i) \
;         __builtin_amdgcn_global_load_lds((const unsigned*)((const char*)(gbase) + (voff)[_i]), (PG8_LAS unsigned*)(lds + (bufoff) + ldsw + _i * 8192), 16, 0, 0); } while (0)
; #define PG8_LDA(dst, b, h) do { _Pragma("unroll") for (int m = 0; m < 4; ++m) _Pragma("unroll") for (int k = 0; k < 2; ++k) dst[m][k] = *(const PG8_LAS bf16x8*)(lds + PG8_SA(b, h) + aoff + m * 2048 + k * 1024); } while (0)
; #define PG8_MMA(ai, bj, At, Bt) do { __builtin_amdgcn_s_setprio(1); _Pragma("unroll") for (int m = 0; m < 4; ++m) _Pragma("unroll") for (int n = 0; n < 2; ++n) _Pragma("unroll") for (int k = 0; k < 2; ++k) \
;         acc[ai][bj][m][n] = __builtin_amdgcn_mfma_f32_16x16x32_bf16(Bt[n][k], At[m][k], acc[ai][bj][m][n], 0, 0, 0); __builtin_amdgcn_s_setprio(0); } while (0)
; #define PG8_WAIT_V(n) asm volatile("s_waitcnt vmcnt(" #n ")" ::: "memory")
; #define PG8_WAIT_L(n) asm volatile("s_waitcnt lgkmcnt(" #n ")" ::: "memory")
; #define PG8_BAR __builtin_amdgcn_s_barrier()
; #define PG8_SCHED __builtin_amdgcn_sched_barrier(0)
; template <class Epi, class Sched, bool ALIGN_EPI = false, bool SP2 = false>
; __device__ __forceinline__ void gemm_phase(PG8_LAS unsigned char* lds, const Gemm g, const Sched& S, const Epi& E) {
;     ...
;             PG8_LDA(At, 0, 1); PG8_STAGE(PG8_SB(0, 0), b2, voffB); PG8_STAGE(PG8_SB(0, 1), b2 + hstep, voffB); PG8_STAGE(PG8_SA(0, 0), a2, voffA);
;             PG8_WAIT_V(8); PG8_WAIT_L(0); PG8_BAR; PG8_MMA(1, 0, At, B0); PG8_MMA(1, 1, At, B1); PG8_BAR; PG8_SCHED;
	s_add_i32 s42, s68, s50
	v_lshl_add_u64 v[218:219], s[6:7], 0, v[156:157]
	s_mov_b32 m0, s42
	ds_read_b128 v[180:183], v216 offset:16384
	ds_read_b128 v[184:187], v216 offset:17408
	ds_read_b128 v[188:191], v216 offset:18432
	ds_read_b128 v[192:195], v216 offset:19456
	ds_read_b128 v[196:199], v216 offset:20480
	ds_read_b128 v[200:203], v216 offset:21504
	ds_read_b128 v[204:207], v216 offset:22528
	ds_read_b128 v[208:211], v216 offset:23552
	global_load_lds_dwordx4 v[218:219], off
	s_add_i32 m0, s42, 0x2000
	s_add_u32 s42, s6, 0x40000
	v_lshl_add_u64 v[222:223], s[6:7], 0, v[160:161]
	s_addc_u32 s43, s7, 0
	s_add_i32 s44, s69, s50
	global_load_lds_dwordx4 v[222:223], off
	v_lshl_add_u64 v[224:225], s[42:43], 0, v[156:157]
	s_mov_b32 m0, s44
	v_lshl_add_u64 v[226:227], s[36:37], 0, v[158:159]
	global_load_lds_dwordx4 v[224:225], off
	v_lshl_add_u64 v[224:225], s[42:43], 0, v[160:161]
	s_add_i32 m0, s44, 0x2000
	s_nop 0
	global_load_lds_dwordx4 v[224:225], off
	v_lshl_add_u64 v[224:225], s[36:37], 0, v[154:155]
	s_mov_b32 m0, s51
	s_nop 0
	global_load_lds_dwordx4 v[224:225], off
	s_mov_b32 m0, s52
	s_nop 0
	global_load_lds_dwordx4 v[226:227], off
	s_waitcnt vmcnt(8)
	s_waitcnt lgkmcnt(0)
	s_barrier
	s_setprio 1
	s_waitcnt lgkmcnt(0)
	v_mfma_f32_16x16x32_bf16 v[78:81], v[50:53], v[180:183], 0
	v_mfma_f32_16x16x32_bf16 v[74:77], v[66:69], v[180:183], 0
	v_mfma_f32_16x16x32_bf16 v[46:49], v[50:53], v[188:191], 0
	v_mfma_f32_16x16x32_bf16 v[42:45], v[66:69], v[188:191], 0
	v_mfma_f32_16x16x32_bf16 v[30:33], v[50:53], v[196:199], 0
	v_mfma_f32_16x16x32_bf16 v[26:29], v[66:69], v[196:199], 0
	v_mfma_f32_16x16x32_bf16 v[14:17], v[50:53], v[204:207], 0
	v_mfma_f32_16x16x32_bf16 v[10:13], v[66:69], v[204:207], 0
	v_mfma_f32_16x16x32_bf16 v[78:81], v[54:57], v[184:187], v[78:81]
	v_mfma_f32_16x16x32_bf16 v[74:77], v[70:73], v[184:187], v[74:77]
	v_mfma_f32_16x16x32_bf16 v[46:49], v[54:57], v[192:195], v[46:49]
	v_mfma_f32_16x16x32_bf16 v[42:45], v[70:73], v[192:195], v[42:45]
	v_mfma_f32_16x16x32_bf16 v[30:33], v[54:57], v[200:203], v[30:33]
	v_mfma_f32_16x16x32_bf16 v[26:29], v[70:73], v[200:203], v[26:29]
	v_mfma_f32_16x16x32_bf16 v[14:17], v[54:57], v[208:211], v[14:17]
	v_mfma_f32_16x16x32_bf16 v[10:13], v[70:73], v[208:211], v[10:13]
	s_setprio 0
	s_setprio 1
	v_mfma_f32_16x16x32_bf16 v[38:41], v[146:149], v[188:191], 0
	v_mfma_f32_16x16x32_bf16 v[34:37], v[172:175], v[188:191], 0
	v_mfma_f32_16x16x32_bf16 v[22:25], v[146:149], v[196:199], 0
	v_mfma_f32_16x16x32_bf16 v[18:21], v[172:175], v[196:199], 0
	v_mfma_f32_16x16x32_bf16 v[6:9], v[146:149], v[204:207], 0
	v_mfma_f32_16x16x32_bf16 v[2:5], v[172:175], v[204:207], 0
	v_mfma_f32_16x16x32_bf16 v[50:53], v[146:149], v[180:183], 0
	v_mfma_f32_16x16x32_bf16 v[54:57], v[172:175], v[180:183], 0
	v_mfma_f32_16x16x32_bf16 v[38:41], v[150:153], v[192:195], v[38:41]
	v_mfma_f32_16x16x32_bf16 v[34:37], v[176:179], v[192:195], v[34:37]
	v_mfma_f32_16x16x32_bf16 v[22:25], v[150:153], v[200:203], v[22:25]
	v_mfma_f32_16x16x32_bf16 v[18:21], v[176:179], v[200:203], v[18:21]
	v_mfma_f32_16x16x32_bf16 v[6:9], v[150:153], v[208:211], v[6:9]
	v_mfma_f32_16x16x32_bf16 v[2:5], v[176:179], v[208:211], v[2:5]
	v_mfma_f32_16x16x32_bf16 v[50:53], v[150:153], v[184:187], v[50:53]
	v_mfma_f32_16x16x32_bf16 v[54:57], v[176:179], v[184:187], v[54:57]
	s_setprio 0
	s_barrier
	s_branch .Lpz4_mid

; #define PG8_STAGE(bufoff, gbase, voff) do { _Pragma("unroll") for (int _i = 0; _i < 2; ++_i) \
;         __builtin_amdgcn_global_load_lds((const unsigned*)((const char*)(gbase) + (voff)[_i]), (PG8_LAS unsigned*)(lds + (bufoff) + ldsw + _i * 8192), 16, 0, 0); } while (0)
; #define PG8_LDA(dst, b, h) do { _Pragma("unroll") for (int m = 0; m < 4; ++m) _Pragma("unroll") for (int k = 0; k < 2; ++k) dst[m][k] = *(const PG8_LAS bf16x8*)(lds + PG8_SA(b, h) + aoff + m * 2048 + k * 1024); } while (0)
; #define PG8_LDB(dst, b, h) do { _Pragma("unroll") for (int n = 0; n < 2; ++n) _Pragma("unroll") for (int k = 0; k < 2; ++k) dst[n][k] = *(const PG8_LAS bf16x8*)(lds + PG8_SB(b, h) + boff + n * 2048 + k * 1024); } while (0)
; #define PG8_MMA(ai, bj, At, Bt) do { __builtin_amdgcn_s_setprio(1); _Pragma("unroll") for (int m = 0; m < 4; ++m) _Pragma("unroll") for (int n = 0; n < 2; ++n) _Pragma("unroll") for (int k = 0; k < 2; ++k) \
;         acc[ai][bj][m][n] = __builtin_amdgcn_mfma_f32_16x16x32_bf16(Bt[n][k], At[m][k], acc[ai][bj][m][n], 0, 0, 0); __builtin_amdgcn_s_setprio(0); } while (0)
; #define PG8_WAIT_V(n) asm volatile("s_waitcnt vmcnt(" #n ")" ::: "memory")
; #define PG8_WAIT_L(n) asm volatile("s_waitcnt lgkmcnt(" #n ")" ::: "memory")
; #define PG8_BAR __builtin_amdgcn_s_barrier()
; #define PG8_SCHED __builtin_amdgcn_sched_barrier(0)
; template <class Epi, class Sched, bool ALIGN_EPI = false, bool SP2 = false>
; __device__ __forceinline__ void gemm_phase(PG8_LAS unsigned char* lds, const Gemm g, const Sched& S, const Epi& E) {
;     ...
;             PG8_LDB(B0, 1, 0); PG8_LDB(B1, 1, 1); PG8_SCHED; PG8_LDA(At, 1, 0); PG8_STAGE(PG8_SA(0, 1), a2 + hstep, voffA);
;             PG8_WAIT_V(8); PG8_WAIT_L(0); PG8_BAR; PG8_MMA(0, 0, At, B0); PG8_MMA(0, 1, At, B1); PG8_BAR; PG8_SCHED;
.Lpz4_mid:
	s_add_i32 s42, 0, 0x18000
	s_add_i32 s43, 0, 0x1c000
	v_add_u32_e32 v70, s42, v213
	v_add_u32_e32 v162, s43, v213
	ds_read_b128 v[58:61], v70
	ds_read_b128 v[62:65], v70 offset:1024
	ds_read_b128 v[66:69], v70 offset:2048
	ds_read_b128 v[70:73], v70 offset:3072
	ds_read_b128 v[146:149], v162
	ds_read_b128 v[150:153], v162 offset:1024
	ds_read_b128 v[172:175], v162 offset:2048
	ds_read_b128 v[176:179], v162 offset:3072
	s_add_u32 s36, s36, 0x40000
	s_addc_u32 s37, s37, 0
	s_mov_b32 m0, s53
	v_lshl_add_u64 v[228:229], s[36:37], 0, v[154:155]
	ds_read_b128 v[180:183], v216 offset:32768
	ds_read_b128 v[184:187], v216 offset:33792
	ds_read_b128 v[188:191], v216 offset:34816
	ds_read_b128 v[192:195], v216 offset:35840
	ds_read_b128 v[196:199], v216 offset:36864
	ds_read_b128 v[200:203], v216 offset:37888
	ds_read_b128 v[204:207], v216 offset:38912
	ds_read_b128 v[208:211], v216 offset:39936
	global_load_lds_dwordx4 v[228:229], off
	v_lshl_add_u64 v[228:229], s[36:37], 0, v[158:159]
	s_mov_b32 m0, s54
	s_nop 0
	global_load_lds_dwordx4 v[228:229], off
	s_waitcnt vmcnt(8)
	s_waitcnt lgkmcnt(0)
	s_barrier
	s_setprio 1
	s_waitcnt lgkmcnt(0)
	v_mfma_f32_16x16x32_bf16 v[142:145], v[58:61], v[180:183], v[142:145]
	v_mfma_f32_16x16x32_bf16 v[138:141], v[66:69], v[180:183], v[138:141]
	v_mfma_f32_16x16x32_bf16 v[126:129], v[58:61], v[188:191], v[126:129]
	v_mfma_f32_16x16x32_bf16 v[122:125], v[66:69], v[188:191], v[122:125]
	v_mfma_f32_16x16x32_bf16 v[110:113], v[58:61], v[196:199], v[110:113]
	v_mfma_f32_16x16x32_bf16 v[106:109], v[66:69], v[196:199], v[106:109]
	v_mfma_f32_16x16x32_bf16 v[94:97], v[58:61], v[204:207], v[94:97]
	v_mfma_f32_16x16x32_bf16 v[90:93], v[66:69], v[204:207], v[90:93]
	v_mfma_f32_16x16x32_bf16 v[142:145], v[62:65], v[184:187], v[142:145]
	v_mfma_f32_16x16x32_bf16 v[138:141], v[70:73], v[184:187], v[138:141]
	v_mfma_f32_16x16x32_bf16 v[126:129], v[62:65], v[192:195], v[126:129]
	v_mfma_f32_16x16x32_bf16 v[122:125], v[70:73], v[192:195], v[122:125]
	v_mfma_f32_16x16x32_bf16 v[110:113], v[62:65], v[200:203], v[110:113]
	v_mfma_f32_16x16x32_bf16 v[106:109], v[70:73], v[200:203], v[106:109]
	v_mfma_f32_16x16x32_bf16 v[94:97], v[62:65], v[208:211], v[94:97]
	v_mfma_f32_16x16x32_bf16 v[90:93], v[70:73], v[208:211], v[90:93]
	s_setprio 0
	s_setprio 1
	v_mfma_f32_16x16x32_bf16 v[134:137], v[146:149], v[180:183], v[134:137]
	v_mfma_f32_16x16x32_bf16 v[130:133], v[172:175], v[180:183], v[130:133]
	v_mfma_f32_16x16x32_bf16 v[118:121], v[146:149], v[188:191], v[118:121]
	v_mfma_f32_16x16x32_bf16 v[114:117], v[172:175], v[188:191], v[114:117]
	v_mfma_f32_16x16x32_bf16 v[102:105], v[146:149], v[196:199], v[102:105]
	v_mfma_f32_16x16x32_bf16 v[98:101], v[172:175], v[196:199], v[98:101]
	v_mfma_f32_16x16x32_bf16 v[86:89], v[146:149], v[204:207], v[86:89]
	v_mfma_f32_16x16x32_bf16 v[82:85], v[172:175], v[204:207], v[82:85]
	v_mfma_f32_16x16x32_bf16 v[134:137], v[150:153], v[184:187], v[134:137]
	v_mfma_f32_16x16x32_bf16 v[130:133], v[176:179], v[184:187], v[130:133]
	v_mfma_f32_16x16x32_bf16 v[118:121], v[150:153], v[192:195], v[118:121]
	v_mfma_f32_16x16x32_bf16 v[114:117], v[176:179], v[192:195], v[114:117]
	v_mfma_f32_16x16x32_bf16 v[102:105], v[150:153], v[200:203], v[102:105]
	v_mfma_f32_16x16x32_bf16 v[98:101], v[176:179], v[200:203], v[98:101]
	v_mfma_f32_16x16x32_bf16 v[86:89], v[150:153], v[208:211], v[86:89]
	v_mfma_f32_16x16x32_bf16 v[82:85], v[176:179], v[208:211], v[82:85]
	s_setprio 0
	s_barrier
; #define PG8_STAGE(bufoff, gbase, voff) do { _Pragma("unroll") for (int _i = 0; _i < 2; ++_i) \
;         __builtin_amdgcn_global_load_lds((const unsigned*)((const char*)(gbase) + (voff)[_i]), (PG8_LAS unsigned*)(lds + (bufoff) + ldsw + _i * 8192), 16, 0, 0); } while (0)
; #define PG8_LDA(dst, b, h) do { _Pragma("unroll") for (int m = 0; m < 4; ++m) _Pragma("unroll") for (int k = 0; k < 2; ++k) dst[m][k] = *(const PG8_LAS bf16x8*)(lds + PG8_SA(b, h) + aoff + m * 2048 + k * 1024); } while (0)
; #define PG8_MMA(ai, bj, At, Bt) do { __builtin_amdgcn_s_setprio(1); _Pragma("unroll") for (int m = 0; m < 4; ++m) _Pragma("unroll") for (int n = 0; n < 2; ++n) _Pragma("unroll") for (int k = 0; k < 2; ++k) \
;         acc[ai][bj][m][n] = __builtin_amdgcn_mfma_f32_16x16x32_bf16(Bt[n][k], At[m][k], acc[ai][bj][m][n], 0, 0, 0); __builtin_amdgcn_s_setprio(0); } while (0)
; #define PG8_WAIT_V(n) asm volatile("s_waitcnt vmcnt(" #n ")" ::: "memory")
; #define PG8_WAIT_L(n) asm volatile("s_waitcnt lgkmcnt(" #n ")" ::: "memory")
; #define PG8_BAR __builtin_amdgcn_s_barrier()
; #define PG8_SCHED __builtin_amdgcn_sched_barrier(0)
; template <class Epi, class Sched, bool ALIGN_EPI = false, bool SP2 = false>
; __device__ __forceinline__ void gemm_phase(PG8_LAS unsigned char* lds, const Gemm g, const Sched& S, const Epi& E) {
;     ...
;             PG8_LDA(At, 1, 1); PG8_STAGE(PG8_SB(1, 0), b3, voffB); PG8_STAGE(PG8_SB(1, 1), b3 + hstep, voffB); PG8_STAGE(PG8_SA(1, 0), a3, voffA);
;             PG8_WAIT_V(8); PG8_WAIT_L(0); PG8_BAR; PG8_MMA(1, 0, At, B0); PG8_MMA(1, 1, At, B1); PG8_BAR; PG8_SCHED;
	s_add_i32 s36, s42, s50
	v_lshl_add_u64 v[218:219], v[218:219], 0, s[20:21]
	s_mov_b32 m0, s36
	ds_read_b128 v[180:183], v216 offset:49152
	ds_read_b128 v[184:187], v216 offset:50176
	ds_read_b128 v[188:191], v216 offset:51200
	ds_read_b128 v[192:195], v216 offset:52224
	ds_read_b128 v[196:199], v216 offset:53248
	ds_read_b128 v[200:203], v216 offset:54272
	ds_read_b128 v[204:207], v216 offset:55296
	ds_read_b128 v[208:211], v216 offset:56320
	global_load_lds_dwordx4 v[218:219], off
	s_add_i32 m0, s36, 0x2000
	s_add_u32 s6, s6, 0x40080
	v_lshl_add_u64 v[218:219], v[222:223], 0, s[20:21]
	s_addc_u32 s7, s7, 0
	s_add_i32 s36, s43, s50
	global_load_lds_dwordx4 v[218:219], off
	v_lshl_add_u64 v[218:219], s[6:7], 0, v[156:157]
	s_mov_b32 m0, s36
	s_nop 0
	global_load_lds_dwordx4 v[218:219], off
	v_lshl_add_u64 v[218:219], s[6:7], 0, v[160:161]
	s_add_i32 m0, s36, 0x2000
	s_nop 0
	global_load_lds_dwordx4 v[218:219], off
	v_lshl_add_u64 v[218:219], v[224:225], 0, s[20:21]
	s_mov_b32 m0, s63
	s_nop 0
	global_load_lds_dwordx4 v[218:219], off
	v_lshl_add_u64 v[218:219], v[226:227], 0, s[20:21]
	s_mov_b32 m0, s64
	s_nop 0
	global_load_lds_dwordx4 v[218:219], off
	s_waitcnt vmcnt(8)
	s_waitcnt lgkmcnt(0)
	s_barrier
	s_setprio 1
	s_waitcnt lgkmcnt(0)
	v_mfma_f32_16x16x32_bf16 v[78:81], v[58:61], v[180:183], v[78:81]
	v_mfma_f32_16x16x32_bf16 v[74:77], v[66:69], v[180:183], v[74:77]
	v_mfma_f32_16x16x32_bf16 v[46:49], v[58:61], v[188:191], v[46:49]
	v_mfma_f32_16x16x32_bf16 v[42:45], v[66:69], v[188:191], v[42:45]
	v_mfma_f32_16x16x32_bf16 v[30:33], v[58:61], v[196:199], v[30:33]
	v_mfma_f32_16x16x32_bf16 v[26:29], v[66:69], v[196:199], v[26:29]
	v_mfma_f32_16x16x32_bf16 v[14:17], v[58:61], v[204:207], v[14:17]
	v_mfma_f32_16x16x32_bf16 v[10:13], v[66:69], v[204:207], v[10:13]
	v_mfma_f32_16x16x32_bf16 v[78:81], v[62:65], v[184:187], v[78:81]
	v_mfma_f32_16x16x32_bf16 v[74:77], v[70:73], v[184:187], v[74:77]
	v_mfma_f32_16x16x32_bf16 v[46:49], v[62:65], v[192:195], v[46:49]
	v_mfma_f32_16x16x32_bf16 v[42:45], v[70:73], v[192:195], v[42:45]
	v_mfma_f32_16x16x32_bf16 v[30:33], v[62:65], v[200:203], v[30:33]
	v_mfma_f32_16x16x32_bf16 v[26:29], v[70:73], v[200:203], v[26:29]
	v_mfma_f32_16x16x32_bf16 v[14:17], v[62:65], v[208:211], v[14:17]
	v_mfma_f32_16x16x32_bf16 v[10:13], v[70:73], v[208:211], v[10:13]
	s_setprio 0
	s_setprio 1
	v_mfma_f32_16x16x32_bf16 v[50:53], v[146:149], v[180:183], v[50:53]
	v_mfma_f32_16x16x32_bf16 v[62:65], v[150:153], v[184:187], v[50:53]
	v_mfma_f32_16x16x32_bf16 v[50:53], v[172:175], v[180:183], v[54:57]
	v_mfma_f32_16x16x32_bf16 v[38:41], v[146:149], v[188:191], v[38:41]
	v_mfma_f32_16x16x32_bf16 v[34:37], v[172:175], v[188:191], v[34:37]
	v_mfma_f32_16x16x32_bf16 v[22:25], v[146:149], v[196:199], v[22:25]
	v_mfma_f32_16x16x32_bf16 v[18:21], v[172:175], v[196:199], v[18:21]
	v_mfma_f32_16x16x32_bf16 v[6:9], v[146:149], v[204:207], v[6:9]
	v_mfma_f32_16x16x32_bf16 v[2:5], v[172:175], v[204:207], v[2:5]
	v_mfma_f32_16x16x32_bf16 v[58:61], v[176:179], v[184:187], v[50:53]
	v_mfma_f32_16x16x32_bf16 v[38:41], v[150:153], v[192:195], v[38:41]
	v_mfma_f32_16x16x32_bf16 v[34:37], v[176:179], v[192:195], v[34:37]
	v_mfma_f32_16x16x32_bf16 v[22:25], v[150:153], v[200:203], v[22:25]
	v_mfma_f32_16x16x32_bf16 v[18:21], v[176:179], v[200:203], v[18:21]
	v_mfma_f32_16x16x32_bf16 v[6:9], v[150:153], v[208:211], v[6:9]
	v_mfma_f32_16x16x32_bf16 v[2:5], v[176:179], v[208:211], v[2:5]
	s_setprio 0
	s_barrier
	s_add_i32 s41, s41, 2
	s_add_u32 s4, s4, 0x100
	s_addc_u32 s5, s5, 0
	s_add_u32 s39, s39, 0x100
	s_addc_u32 s40, s40, 0
	s_cmp_gt_u32 s41, 13
	s_cbranch_scc0 .LBB0_838
	s_and_b64 vcc, exec, s[22:23]
	s_cbranch_vccz .LBB0_841
	s_barrier

; #define PG8_LAS __attribute__((address_space(3)))
;     __host__ __device__ bool next(int i, Unit& u) const { if (!b.next(i >> 1, u)) return false; u.sel = i & 1; return true; }
; #define PG8_STAGE(bufoff, gbase, voff) do { _Pragma("unroll") for (int _i = 0; _i < 2; ++_i) \
;         __builtin_amdgcn_global_load_lds((const unsigned*)((const char*)(gbase) + (voff)[_i]), (PG8_LAS unsigned*)(lds + (bufoff) + ldsw + _i * 8192), 16, 0, 0); } while (0)
; #define PG8_WAIT_V(n) asm volatile("s_waitcnt vmcnt(" #n ")" ::: "memory")
; #define PG8_WAIT_L(n) asm volatile("s_waitcnt lgkmcnt(" #n ")" ::: "memory")
; template <class Epi, class Sched, bool ALIGN_EPI = false, bool SP2 = false>
; __device__ __forceinline__ void gemm_phase(PG8_LAS unsigned char* lds, const Gemm g, const Sched& S, const Epi& E) {
;     ...
;         const bool has_next = S.next(ui + 1, nxt);
;         const char* nA = has_next ? PG8_ABASE(nxt) : cA; const char* nB = has_next ? PG8_BBASE(nxt) : cB;
;         for (int t = 0; t < nt; t += 2) {
;             const bool last = (t == nt - 2);
;             const char* a1 = cA + (size_t)(t + 1) * kstepA;
;             const char* a2 = last ? nA : cA + (size_t)(t + 2) * kstepA; const char* b2 = last ? nB : cB + (size_t)(t + 2) * kstep;
;             const char* a3 = a2 + kstepA; const char* b3 = b2 + kstep;
;             if (last && has_next) S.a_ready(nxt);
;             if constexpr (SP2) {
;             PG8_LDB(B0, 0, 0); PG8_LDB(B1, 0, 1); PG8_SCHED; PG8_LDA(At, 0, 0); PG8_STAGE(PG8_SA(1, 1), a1 + hstep, voffA);
;             PG8_WAIT_V(8); PG8_WAIT_L(0); PG8_BAR; PG8_MMA(0, 0, At, B0); PG8_MMA(0, 1, At, B1); PG8_BAR; PG8_SCHED;
;             if constexpr (Epi::PREFETCH) { if (t == tpf) E.prefetch(cur, wid, lane); }
; __device__ __forceinline__ void epi_prefetch(PG8_LAS unsigned char* scr, const float* ssq, const float* bias_tile, const Unit& u, int wid, int lane) {
;     unsigned lo = (unsigned)lane * 16u; asm volatile("" : "+v"(lo));
;     const char* src = (const char*)(ssq + (size_t)u.pm * BM * 16 + wid * 512);
; #pragma unroll
;     for (int j = 0; j < 2; ++j) __builtin_amdgcn_global_load_lds((const unsigned*)(src + j * 1024 + lo), (PG8_LAS unsigned*)(scr + (wid * 2 + j) * 1024), 16, 0, 0);
;     if (wid == 0) __builtin_amdgcn_global_load_lds((const unsigned*)((const char*)bias_tile + lo), (PG8_LAS unsigned*)(scr + 16384), 16, 0, 0);
; }
.LBB0_984:
	s_ashr_i32 s23, s22, 31
	s_lshl_b64 s[24:25], s[22:23], 19
	s_add_u32 s24, s47, s24
	s_addc_u32 s25, s48, s25
	s_and_b64 s[26:27], s[2:3], exec
	s_cselect_b32 s23, s25, s31
	s_cselect_b32 s81, s24, s30
	s_ashr_i32 s21, s20, 31
	s_lshl_b64 s[26:27], s[20:21], 19
	s_add_u32 s26, s49, s26
	s_addc_u32 s27, s50, s27
	s_and_b64 s[36:37], s[2:3], exec
	s_cselect_b32 s21, s27, s41
	s_cselect_b32 s82, s26, s40
	s_ashr_i32 s29, s28, 31
	s_lshl_b32 s34, s34, 8
	s_lshl_b64 s[36:37], s[28:29], 14
	s_ashr_i32 s29, s28, 5
	s_ashr_i32 s35, s34, 31
	s_add_u32 s36, s10, s36
	s_mul_hi_i32 s38, s29, 0x5800
	s_mulk_i32 s29, 0x5800
	s_addc_u32 s37, s69, s37
	s_add_u32 s29, s62, s29
	s_addc_u32 s42, s63, s38
	s_lshl_b64 s[38:39], s[34:35], 2
	s_add_u32 s38, s29, s38
	s_addc_u32 s39, s42, s39
	s_add_u32 s29, s40, 0x100
	v_lshl_add_u64 v[188:189], s[30:31], 0, v[180:181]
	v_lshl_add_u64 v[190:191], s[30:31], 0, v[182:183]
	s_addc_u32 s35, s41, 0
	s_mov_b32 s83, 0
	s_mov_b64 s[40:41], 0
	ds_read_b128 v[154:157], v195
	ds_read_b128 v[158:161], v195 offset:1024
	ds_read_b128 v[162:165], v195 offset:2048
	ds_read_b128 v[166:169], v195 offset:3072
	ds_read_b128 v[138:141], v196
	ds_read_b128 v[142:145], v196 offset:1024
	ds_read_b128 v[146:149], v196 offset:2048
	ds_read_b128 v[150:153], v196 offset:3072
	v_lshl_add_u64 v[98:99], v[188:189], 0, s[40:41]
	s_add_i32 m0, s54, 0xc000
	ds_read_b128 v[200:203], v197
	ds_read_b128 v[204:207], v197 offset:1024
	ds_read_b128 v[208:211], v197 offset:2048
	ds_read_b128 v[212:215], v197 offset:3072
	ds_read_b128 v[216:219], v197 offset:4096
	ds_read_b128 v[220:223], v197 offset:5120
	ds_read_b128 v[224:227], v197 offset:6144
	ds_read_b128 v[228:231], v197 offset:7168
	global_load_lds_dwordx4 v[98:99], off
	v_lshl_add_u64 v[98:99], v[190:191], 0, s[40:41]
	s_add_i32 m0, s54, 0xe000
	s_nop 0
	global_load_lds_dwordx4 v[98:99], off
	s_waitcnt vmcnt(8)
	s_waitcnt lgkmcnt(0)
	s_barrier
	s_setprio 1
	s_waitcnt lgkmcnt(0)
	v_mfma_f32_16x16x32_bf16 v[98:101], v[154:157], v[200:203], 0
	v_mfma_f32_16x16x32_bf16 v[106:109], v[162:165], v[200:203], 0
	v_mfma_f32_16x16x32_bf16 v[118:121], v[154:157], v[208:211], 0
	v_mfma_f32_16x16x32_bf16 v[114:117], v[162:165], v[208:211], 0
	v_mfma_f32_16x16x32_bf16 v[94:97], v[154:157], v[216:219], 0
	v_mfma_f32_16x16x32_bf16 v[90:93], v[162:165], v[216:219], 0
	v_mfma_f32_16x16x32_bf16 v[78:81], v[154:157], v[224:227], 0
	v_mfma_f32_16x16x32_bf16 v[74:77], v[162:165], v[224:227], 0
	v_mfma_f32_16x16x32_bf16 v[98:101], v[158:161], v[204:207], v[98:101]
	v_mfma_f32_16x16x32_bf16 v[106:109], v[166:169], v[204:207], v[106:109]
	v_mfma_f32_16x16x32_bf16 v[118:121], v[158:161], v[212:215], v[118:121]
	v_mfma_f32_16x16x32_bf16 v[114:117], v[166:169], v[212:215], v[114:117]
	v_mfma_f32_16x16x32_bf16 v[94:97], v[158:161], v[220:223], v[94:97]
	v_mfma_f32_16x16x32_bf16 v[90:93], v[166:169], v[220:223], v[90:93]
	v_mfma_f32_16x16x32_bf16 v[78:81], v[158:161], v[228:231], v[78:81]
	v_mfma_f32_16x16x32_bf16 v[74:77], v[166:169], v[228:231], v[74:77]
	s_setprio 0
	s_setprio 1
	v_mfma_f32_16x16x32_bf16 v[126:129], v[138:141], v[200:203], 0
	v_mfma_f32_16x16x32_bf16 v[122:125], v[146:149], v[200:203], 0
	v_mfma_f32_16x16x32_bf16 v[110:113], v[138:141], v[208:211], 0
	v_mfma_f32_16x16x32_bf16 v[102:105], v[146:149], v[208:211], 0
	v_mfma_f32_16x16x32_bf16 v[86:89], v[138:141], v[216:219], 0
	v_mfma_f32_16x16x32_bf16 v[82:85], v[146:149], v[216:219], 0
	v_mfma_f32_16x16x32_bf16 v[70:73], v[138:141], v[224:227], 0
	v_mfma_f32_16x16x32_bf16 v[66:69], v[146:149], v[224:227], 0
	v_mfma_f32_16x16x32_bf16 v[126:129], v[142:145], v[204:207], v[126:129]
	v_mfma_f32_16x16x32_bf16 v[122:125], v[150:153], v[204:207], v[122:125]
	v_mfma_f32_16x16x32_bf16 v[110:113], v[142:145], v[212:215], v[110:113]
	v_mfma_f32_16x16x32_bf16 v[102:105], v[150:153], v[212:215], v[102:105]
	v_mfma_f32_16x16x32_bf16 v[86:89], v[142:145], v[220:223], v[86:89]
	v_mfma_f32_16x16x32_bf16 v[82:85], v[150:153], v[220:223], v[82:85]
	v_mfma_f32_16x16x32_bf16 v[70:73], v[142:145], v[228:231], v[70:73]
	v_mfma_f32_16x16x32_bf16 v[66:69], v[150:153], v[228:231], v[66:69]
	s_setprio 0
	s_barrier
	s_cmp_lg_u32 s46, s83
	s_cbranch_scc1 .Lpz5_a
	v_mov_b32_e32 v178, v194
	s_add_i32 m0, s79, 0x20000
	v_lshl_add_u64 v[130:131], s[36:37], 0, v[178:179]
	global_load_lds_dwordx4 v178, s[36:37]
	v_lshl_add_u64 v[130:131], v[130:131], 0, s[18:19]
	s_add_i32 m0, s79, 0x20400
	s_andn2_b64 vcc, exec, s[14:15]
	global_load_lds_dwordx4 v[130:131], off
	s_cbranch_vccnz .Lpz5_a
	v_lshl_add_u64 v[130:131], s[38:39], 0, v[178:179]
	s_add_i32 m0, 0, 0x24000
	s_nop 0
	global_load_lds_dwordx4 v[130:131], off
	s_branch .Lpz5_a
; #define PG8_STAGE(bufoff, gbase, voff) do { _Pragma("unroll") for (int _i = 0; _i < 2; ++_i) \
;         __builtin_amdgcn_global_load_lds((const unsigned*)((const char*)(gbase) + (voff)[_i]), (PG8_LAS unsigned*)(lds + (bufoff) + ldsw + _i * 8192), 16, 0, 0); } while (0)
; #define PG8_LDA(dst, b, h) do { _Pragma("unroll") for (int m = 0; m < 4; ++m) _Pragma("unroll") for (int k = 0; k < 2; ++k) dst[m][k] = *(const PG8_LAS bf16x8*)(lds + PG8_SA(b, h) + aoff + m * 2048 + k * 1024); } while (0)
; #define PG8_LDB(dst, b, h) do { _Pragma("unroll") for (int n = 0; n < 2; ++n) _Pragma("unroll") for (int k = 0; k < 2; ++k) dst[n][k] = *(const PG8_LAS bf16x8*)(lds + PG8_SB(b, h) + boff + n * 2048 + k * 1024); } while (0)
; #define PG8_MMA(ai, bj, At, Bt) do { __builtin_amdgcn_s_setprio(1); _Pragma("unroll") for (int m = 0; m < 4; ++m) _Pragma("unroll") for (int n = 0; n < 2; ++n) _Pragma("unroll") for (int k = 0; k < 2; ++k) \
;         acc[ai][bj][m][n] = __builtin_amdgcn_mfma_f32_16x16x32_bf16(Bt[n][k], At[m][k], acc[ai][bj][m][n], 0, 0, 0); __builtin_amdgcn_s_setprio(0); } while (0)
; #define PG8_WAIT_V(n) asm volatile("s_waitcnt vmcnt(" #n ")" ::: "memory")
; template <class Epi, class Sched, bool ALIGN_EPI = false, bool SP2 = false>
; __device__ __forceinline__ void gemm_phase(PG8_LAS unsigned char* lds, const Gemm g, const Sched& S, const Epi& E) {
;     ...
;             const bool last = (t == nt - 2);
;             const char* a1 = cA + (size_t)(t + 1) * kstepA;
;             const char* a2 = last ? nA : cA + (size_t)(t + 2) * kstepA; const char* b2 = last ? nB : cB + (size_t)(t + 2) * kstep;
;             const char* a3 = a2 + kstepA; const char* b3 = b2 + kstep;
;             if (last && has_next) S.a_ready(nxt);
;             if constexpr (SP2) {
;             PG8_LDB(B0, 0, 0); PG8_LDB(B1, 0, 1); PG8_SCHED; PG8_LDA(At, 0, 0); PG8_STAGE(PG8_SA(1, 1), a1 + hstep, voffA);
;             PG8_WAIT_V(8); PG8_WAIT_L(0); PG8_BAR; PG8_MMA(0, 0, At, B0); PG8_MMA(0, 1, At, B1); PG8_BAR; PG8_SCHED;
;             if constexpr (Epi::PREFETCH) { if (t == tpf) E.prefetch(cur, wid, lane); }
;             PG8_LDA(At, 0, 1); PG8_STAGE(PG8_SB(0, 0), b2, voffB); PG8_STAGE(PG8_SB(0, 1), b2 + hstep, voffB); PG8_STAGE(PG8_SA(0, 0), a2, voffA);
;             PG8_WAIT_V(8); PG8_WAIT_L(0); PG8_BAR; PG8_MMA(1, 0, At, B0); PG8_MMA(1, 1, At, B1); PG8_BAR; PG8_SCHED;
.Lpz5_a:
	s_add_u32 s42, s30, s40
	s_addc_u32 s43, s31, s41
	s_add_u32 s42, s42, 0x100
	s_addc_u32 s43, s43, 0
	s_add_u32 s84, s29, s40
	s_addc_u32 s85, s35, s41
	s_cmpk_eq_i32 s40, 0x700
	s_cselect_b32 s45, s23, s43
	s_cselect_b32 s44, s81, s42
	s_cselect_b32 s43, s21, s85
	s_cselect_b32 s42, s82, s84
	s_mov_b32 m0, s55
	v_lshl_add_u64 v[232:233], s[42:43], 0, v[174:175]
	s_add_u32 s84, s42, 0x40000
	ds_read_b128 v[130:133], v197 offset:16384
	ds_read_b128 v[134:137], v197 offset:17408
	ds_read_b128 v[200:203], v197 offset:18432
	ds_read_b128 v[204:207], v197 offset:19456
	ds_read_b128 v[208:211], v197 offset:20480
	ds_read_b128 v[212:215], v197 offset:21504
	ds_read_b128 v[216:219], v197 offset:22528
	ds_read_b128 v[220:223], v197 offset:23552
	global_load_lds_dwordx4 v[232:233], off
	v_lshl_add_u64 v[234:235], s[42:43], 0, v[170:171]
	s_mov_b32 m0, s56
	s_addc_u32 s85, s43, 0
	global_load_lds_dwordx4 v[234:235], off
	v_lshl_add_u64 v[224:225], s[84:85], 0, v[174:175]
	s_mov_b32 m0, s57
	v_lshl_add_u64 v[236:237], s[44:45], 0, v[176:177]
	global_load_lds_dwordx4 v[224:225], off
	v_lshl_add_u64 v[224:225], s[84:85], 0, v[170:171]
	s_mov_b32 m0, s58
	v_lshl_add_u64 v[238:239], s[44:45], 0, v[172:173]
	global_load_lds_dwordx4 v[224:225], off
	s_mov_b32 m0, s54
	s_nop 0
	global_load_lds_dwordx4 v[236:237], off
	s_mov_b32 m0, s59
	s_nop 0
	global_load_lds_dwordx4 v[238:239], off
	s_waitcnt vmcnt(8)
	s_waitcnt lgkmcnt(0)
	s_barrier
	s_setprio 1
	s_waitcnt lgkmcnt(0)
	v_mfma_f32_16x16x32_bf16 v[62:65], v[154:157], v[130:133], 0
	v_mfma_f32_16x16x32_bf16 v[58:61], v[162:165], v[130:133], 0
	v_mfma_f32_16x16x32_bf16 v[46:49], v[154:157], v[200:203], 0
	v_mfma_f32_16x16x32_bf16 v[42:45], v[162:165], v[200:203], 0
	v_mfma_f32_16x16x32_bf16 v[30:33], v[154:157], v[208:211], 0
	v_mfma_f32_16x16x32_bf16 v[26:29], v[162:165], v[208:211], 0
	v_mfma_f32_16x16x32_bf16 v[14:17], v[154:157], v[216:219], 0
	v_mfma_f32_16x16x32_bf16 v[10:13], v[162:165], v[216:219], 0
	v_mfma_f32_16x16x32_bf16 v[62:65], v[158:161], v[134:137], v[62:65]
	v_mfma_f32_16x16x32_bf16 v[58:61], v[166:169], v[134:137], v[58:61]
	v_mfma_f32_16x16x32_bf16 v[46:49], v[158:161], v[204:207], v[46:49]
	v_mfma_f32_16x16x32_bf16 v[42:45], v[166:169], v[204:207], v[42:45]
	v_mfma_f32_16x16x32_bf16 v[30:33], v[158:161], v[212:215], v[30:33]
	v_mfma_f32_16x16x32_bf16 v[26:29], v[166:169], v[212:215], v[26:29]
	v_mfma_f32_16x16x32_bf16 v[14:17], v[158:161], v[220:223], v[14:17]
	v_mfma_f32_16x16x32_bf16 v[10:13], v[166:169], v[220:223], v[10:13]
	s_setprio 0
	s_setprio 1
	v_mfma_f32_16x16x32_bf16 v[54:57], v[138:141], v[130:133], 0
	v_mfma_f32_16x16x32_bf16 v[50:53], v[146:149], v[130:133], 0
	v_mfma_f32_16x16x32_bf16 v[38:41], v[138:141], v[200:203], 0
	v_mfma_f32_16x16x32_bf16 v[34:37], v[146:149], v[200:203], 0
	v_mfma_f32_16x16x32_bf16 v[22:25], v[138:141], v[208:211], 0
	v_mfma_f32_16x16x32_bf16 v[18:21], v[146:149], v[208:211], 0
	v_mfma_f32_16x16x32_bf16 v[6:9], v[138:141], v[216:219], 0
	v_mfma_f32_16x16x32_bf16 v[2:5], v[146:149], v[216:219], 0
	v_mfma_f32_16x16x32_bf16 v[54:57], v[142:145], v[134:137], v[54:57]
	v_mfma_f32_16x16x32_bf16 v[50:53], v[150:153], v[134:137], v[50:53]
	v_mfma_f32_16x16x32_bf16 v[38:41], v[142:145], v[204:207], v[38:41]
	v_mfma_f32_16x16x32_bf16 v[34:37], v[150:153], v[204:207], v[34:37]
	v_mfma_f32_16x16x32_bf16 v[22:25], v[142:145], v[212:215], v[22:25]
	v_mfma_f32_16x16x32_bf16 v[18:21], v[150:153], v[212:215], v[18:21]
	v_mfma_f32_16x16x32_bf16 v[6:9], v[142:145], v[220:223], v[6:9]
	v_mfma_f32_16x16x32_bf16 v[2:5], v[150:153], v[220:223], v[2:5]
	s_setprio 0
	s_barrier
	s_branch .Lpz5_mid

; #define PG8_STAGE(bufoff, gbase, voff) do { _Pragma("unroll") for (int _i = 0; _i < 2; ++_i) \
;         __builtin_amdgcn_global_load_lds((const unsigned*)((const char*)(gbase) + (voff)[_i]), (PG8_LAS unsigned*)(lds + (bufoff) + ldsw + _i * 8192), 16, 0, 0); } while (0)
; #define PG8_LDA(dst, b, h) do { _Pragma("unroll") for (int m = 0; m < 4; ++m) _Pragma("unroll") for (int k = 0; k < 2; ++k) dst[m][k] = *(const PG8_LAS bf16x8*)(lds + PG8_SA(b, h) + aoff + m * 2048 + k * 1024); } while (0)
; #define PG8_LDB(dst, b, h) do { _Pragma("unroll") for (int n = 0; n < 2; ++n) _Pragma("unroll") for (int k = 0; k < 2; ++k) dst[n][k] = *(const PG8_LAS bf16x8*)(lds + PG8_SB(b, h) + boff + n * 2048 + k * 1024); } while (0)
; #define PG8_MMA(ai, bj, At, Bt) do { __builtin_amdgcn_s_setprio(1); _Pragma("unroll") for (int m = 0; m < 4; ++m) _Pragma("unroll") for (int n = 0; n < 2; ++n) _Pragma("unroll") for (int k = 0; k < 2; ++k) \
;         acc[ai][bj][m][n] = __builtin_amdgcn_mfma_f32_16x16x32_bf16(Bt[n][k], At[m][k], acc[ai][bj][m][n], 0, 0, 0); __builtin_amdgcn_s_setprio(0); } while (0)
; #define PG8_WAIT_V(n) asm volatile("s_waitcnt vmcnt(" #n ")" ::: "memory")
; #define PG8_WAIT_L(n) asm volatile("s_waitcnt lgkmcnt(" #n ")" ::: "memory")
; #define PG8_BAR __builtin_amdgcn_s_barrier()
; #define PG8_SCHED __builtin_amdgcn_sched_barrier(0)
; template <class Epi, class Sched, bool ALIGN_EPI = false, bool SP2 = false>
; __device__ __forceinline__ void gemm_phase(PG8_LAS unsigned char* lds, const Gemm g, const Sched& S, const Epi& E) {
;     ...
;             PG8_LDB(B0, 1, 0); PG8_LDB(B1, 1, 1); PG8_SCHED; PG8_LDA(At, 1, 0); PG8_STAGE(PG8_SA(0, 1), a2 + hstep, voffA);
;             PG8_WAIT_V(8); PG8_WAIT_L(0); PG8_BAR; PG8_MMA(0, 0, At, B0); PG8_MMA(0, 1, At, B1); PG8_BAR; PG8_SCHED;
.Lpz5_mid:
	s_add_i32 s84, 0, 0x18000
	v_add_u32_e32 v130, s84, v193
	s_add_i32 s85, 0, 0x1c000
	ds_read_b128 v[138:141], v130
	ds_read_b128 v[142:145], v130 offset:1024
	ds_read_b128 v[146:149], v130 offset:2048
	ds_read_b128 v[150:153], v130 offset:3072
	v_add_u32_e32 v130, s85, v193
	ds_read_b128 v[154:157], v130
	ds_read_b128 v[158:161], v130 offset:1024
	ds_read_b128 v[162:165], v130 offset:2048
	ds_read_b128 v[166:169], v130 offset:3072
	s_add_u32 s44, s44, 0x40000
	s_addc_u32 s45, s45, 0
	s_mov_b32 m0, s60
	v_lshl_add_u64 v[130:131], s[44:45], 0, v[176:177]
	ds_read_b128 v[200:203], v197 offset:32768
	ds_read_b128 v[204:207], v197 offset:33792
	ds_read_b128 v[208:211], v197 offset:34816
	ds_read_b128 v[212:215], v197 offset:35840
	ds_read_b128 v[216:219], v197 offset:36864
	ds_read_b128 v[220:223], v197 offset:37888
	ds_read_b128 v[224:227], v197 offset:38912
	ds_read_b128 v[228:231], v197 offset:39936
	global_load_lds_dwordx4 v[130:131], off
	v_lshl_add_u64 v[130:131], s[44:45], 0, v[172:173]
	s_mov_b32 m0, s61
	s_nop 0
	global_load_lds_dwordx4 v[130:131], off
	s_waitcnt vmcnt(8)
	s_waitcnt lgkmcnt(0)
	s_barrier
	s_setprio 1
	s_waitcnt lgkmcnt(0)
	v_mfma_f32_16x16x32_bf16 v[98:101], v[138:141], v[200:203], v[98:101]
	v_mfma_f32_16x16x32_bf16 v[134:137], v[142:145], v[204:207], v[98:101]
	v_mfma_f32_16x16x32_bf16 v[98:101], v[146:149], v[200:203], v[106:109]
	v_mfma_f32_16x16x32_bf16 v[130:133], v[150:153], v[204:207], v[98:101]
	v_mfma_f32_16x16x32_bf16 v[98:101], v[138:141], v[208:211], v[118:121]
	v_mfma_f32_16x16x32_bf16 v[118:121], v[142:145], v[212:215], v[98:101]
	v_mfma_f32_16x16x32_bf16 v[98:101], v[146:149], v[208:211], v[114:117]
	v_mfma_f32_16x16x32_bf16 v[94:97], v[138:141], v[216:219], v[94:97]
	v_mfma_f32_16x16x32_bf16 v[90:93], v[146:149], v[216:219], v[90:93]
	v_mfma_f32_16x16x32_bf16 v[78:81], v[138:141], v[224:227], v[78:81]
	v_mfma_f32_16x16x32_bf16 v[74:77], v[146:149], v[224:227], v[74:77]
	v_mfma_f32_16x16x32_bf16 v[114:117], v[150:153], v[212:215], v[98:101]
	v_mfma_f32_16x16x32_bf16 v[94:97], v[142:145], v[220:223], v[94:97]
	v_mfma_f32_16x16x32_bf16 v[90:93], v[150:153], v[220:223], v[90:93]
	v_mfma_f32_16x16x32_bf16 v[78:81], v[142:145], v[228:231], v[78:81]
	v_mfma_f32_16x16x32_bf16 v[74:77], v[150:153], v[228:231], v[74:77]
	s_setprio 0
	s_setprio 1
	v_mfma_f32_16x16x32_bf16 v[98:101], v[154:157], v[200:203], v[126:129]
	v_mfma_f32_16x16x32_bf16 v[126:129], v[158:161], v[204:207], v[98:101]
	v_mfma_f32_16x16x32_bf16 v[98:101], v[162:165], v[200:203], v[122:125]
	v_mfma_f32_16x16x32_bf16 v[122:125], v[166:169], v[204:207], v[98:101]
	v_mfma_f32_16x16x32_bf16 v[98:101], v[154:157], v[208:211], v[110:113]
	v_mfma_f32_16x16x32_bf16 v[110:113], v[158:161], v[212:215], v[98:101]
	v_mfma_f32_16x16x32_bf16 v[98:101], v[162:165], v[208:211], v[102:105]
	v_mfma_f32_16x16x32_bf16 v[86:89], v[154:157], v[216:219], v[86:89]
	v_mfma_f32_16x16x32_bf16 v[82:85], v[162:165], v[216:219], v[82:85]
	v_mfma_f32_16x16x32_bf16 v[70:73], v[154:157], v[224:227], v[70:73]
	v_mfma_f32_16x16x32_bf16 v[66:69], v[162:165], v[224:227], v[66:69]
	v_mfma_f32_16x16x32_bf16 v[102:105], v[166:169], v[212:215], v[98:101]
	v_mfma_f32_16x16x32_bf16 v[86:89], v[158:161], v[220:223], v[86:89]
	v_mfma_f32_16x16x32_bf16 v[82:85], v[166:169], v[220:223], v[82:85]
	v_mfma_f32_16x16x32_bf16 v[70:73], v[158:161], v[228:231], v[70:73]
	v_mfma_f32_16x16x32_bf16 v[66:69], v[166:169], v[228:231], v[66:69]
	s_setprio 0
	s_barrier
; #define PG8_STAGE(bufoff, gbase, voff) do { _Pragma("unroll") for (int _i = 0; _i < 2; ++_i) \
;         __builtin_amdgcn_global_load_lds((const unsigned*)((const char*)(gbase) + (voff)[_i]), (PG8_LAS unsigned*)(lds + (bufoff) + ldsw + _i * 8192), 16, 0, 0); } while (0)
; #define PG8_LDA(dst, b, h) do { _Pragma("unroll") for (int m = 0; m < 4; ++m) _Pragma("unroll") for (int k = 0; k < 2; ++k) dst[m][k] = *(const PG8_LAS bf16x8*)(lds + PG8_SA(b, h) + aoff + m * 2048 + k * 1024); } while (0)
; #define PG8_MMA(ai, bj, At, Bt) do { __builtin_amdgcn_s_setprio(1); _Pragma("unroll") for (int m = 0; m < 4; ++m) _Pragma("unroll") for (int n = 0; n < 2; ++n) _Pragma("unroll") for (int k = 0; k < 2; ++k) \
;         acc[ai][bj][m][n] = __builtin_amdgcn_mfma_f32_16x16x32_bf16(Bt[n][k], At[m][k], acc[ai][bj][m][n], 0, 0, 0); __builtin_amdgcn_s_setprio(0); } while (0)
; #define PG8_WAIT_V(n) asm volatile("s_waitcnt vmcnt(" #n ")" ::: "memory")
; #define PG8_WAIT_L(n) asm volatile("s_waitcnt lgkmcnt(" #n ")" ::: "memory")
; #define PG8_BAR __builtin_amdgcn_s_barrier()
; #define PG8_SCHED __builtin_amdgcn_sched_barrier(0)
; template <class Epi, class Sched, bool ALIGN_EPI = false, bool SP2 = false>
; __device__ __forceinline__ void gemm_phase(PG8_LAS unsigned char* lds, const Gemm g, const Sched& S, const Epi& E) {
;     ...
;         for (int t = 0; t < nt; t += 2) {
;             const bool last = (t == nt - 2);
;             const char* a1 = cA + (size_t)(t + 1) * kstepA;
;             const char* a2 = last ? nA : cA + (size_t)(t + 2) * kstepA; const char* b2 = last ? nB : cB + (size_t)(t + 2) * kstep;
;     ...
;             PG8_LDA(At, 1, 1); PG8_STAGE(PG8_SB(1, 0), b3, voffB); PG8_STAGE(PG8_SB(1, 1), b3 + hstep, voffB); PG8_STAGE(PG8_SA(1, 0), a3, voffA);
;             PG8_WAIT_V(8); PG8_WAIT_L(0); PG8_BAR; PG8_MMA(1, 0, At, B0); PG8_MMA(1, 1, At, B1); PG8_BAR; PG8_SCHED;
	s_add_i32 s44, s84, s51
	v_lshl_add_u64 v[224:225], v[232:233], 0, s[8:9]
	s_mov_b32 m0, s44
	ds_read_b128 v[98:101], v197 offset:49152
	ds_read_b128 v[106:109], v197 offset:50176
	ds_read_b128 v[200:203], v197 offset:51200
	ds_read_b128 v[204:207], v197 offset:52224
	ds_read_b128 v[208:211], v197 offset:53248
	ds_read_b128 v[212:215], v197 offset:54272
	ds_read_b128 v[216:219], v197 offset:55296
	ds_read_b128 v[220:223], v197 offset:56320
	global_load_lds_dwordx4 v[224:225], off
	s_add_i32 m0, s44, 0x2000
	s_add_u32 s42, s42, 0x40080
	v_lshl_add_u64 v[224:225], v[234:235], 0, s[8:9]
	s_addc_u32 s43, s43, 0
	s_add_i32 s44, s85, s51
	global_load_lds_dwordx4 v[224:225], off
	v_lshl_add_u64 v[224:225], s[42:43], 0, v[174:175]
	s_mov_b32 m0, s44
	s_nop 0
	global_load_lds_dwordx4 v[224:225], off
	v_lshl_add_u64 v[224:225], s[42:43], 0, v[170:171]
	s_add_i32 m0, s44, 0x2000
	s_nop 0
	global_load_lds_dwordx4 v[224:225], off
	v_lshl_add_u64 v[224:225], v[236:237], 0, s[8:9]
	s_mov_b32 m0, s65
	s_nop 0
	global_load_lds_dwordx4 v[224:225], off
	v_lshl_add_u64 v[224:225], v[238:239], 0, s[8:9]
	s_mov_b32 m0, s66
	s_nop 0
	global_load_lds_dwordx4 v[224:225], off
	s_waitcnt vmcnt(8)
	s_waitcnt lgkmcnt(0)
	s_barrier
	s_setprio 1
	s_waitcnt lgkmcnt(0)
	v_mfma_f32_16x16x32_bf16 v[62:65], v[138:141], v[98:101], v[62:65]
	v_mfma_f32_16x16x32_bf16 v[58:61], v[146:149], v[98:101], v[58:61]
	v_mfma_f32_16x16x32_bf16 v[46:49], v[138:141], v[200:203], v[46:49]
	v_mfma_f32_16x16x32_bf16 v[42:45], v[146:149], v[200:203], v[42:45]
	v_mfma_f32_16x16x32_bf16 v[30:33], v[138:141], v[208:211], v[30:33]
	v_mfma_f32_16x16x32_bf16 v[26:29], v[146:149], v[208:211], v[26:29]
	v_mfma_f32_16x16x32_bf16 v[14:17], v[138:141], v[216:219], v[14:17]
	v_mfma_f32_16x16x32_bf16 v[10:13], v[146:149], v[216:219], v[10:13]
	v_mfma_f32_16x16x32_bf16 v[62:65], v[142:145], v[106:109], v[62:65]
	v_mfma_f32_16x16x32_bf16 v[58:61], v[150:153], v[106:109], v[58:61]
	v_mfma_f32_16x16x32_bf16 v[46:49], v[142:145], v[204:207], v[46:49]
	v_mfma_f32_16x16x32_bf16 v[42:45], v[150:153], v[204:207], v[42:45]
	v_mfma_f32_16x16x32_bf16 v[30:33], v[142:145], v[212:215], v[30:33]
	v_mfma_f32_16x16x32_bf16 v[26:29], v[150:153], v[212:215], v[26:29]
	v_mfma_f32_16x16x32_bf16 v[14:17], v[142:145], v[220:223], v[14:17]
	v_mfma_f32_16x16x32_bf16 v[10:13], v[150:153], v[220:223], v[10:13]
	s_setprio 0
	s_setprio 1
	v_mfma_f32_16x16x32_bf16 v[54:57], v[154:157], v[98:101], v[54:57]
	v_mfma_f32_16x16x32_bf16 v[50:53], v[162:165], v[98:101], v[50:53]
	v_mfma_f32_16x16x32_bf16 v[38:41], v[154:157], v[200:203], v[38:41]
	v_mfma_f32_16x16x32_bf16 v[34:37], v[162:165], v[200:203], v[34:37]
	v_mfma_f32_16x16x32_bf16 v[22:25], v[154:157], v[208:211], v[22:25]
	v_mfma_f32_16x16x32_bf16 v[18:21], v[162:165], v[208:211], v[18:21]
	v_mfma_f32_16x16x32_bf16 v[6:9], v[154:157], v[216:219], v[6:9]
	v_mfma_f32_16x16x32_bf16 v[2:5], v[162:165], v[216:219], v[2:5]
	v_mfma_f32_16x16x32_bf16 v[54:57], v[158:161], v[106:109], v[54:57]
	v_mfma_f32_16x16x32_bf16 v[50:53], v[166:169], v[106:109], v[50:53]
	v_mfma_f32_16x16x32_bf16 v[38:41], v[158:161], v[204:207], v[38:41]
	v_mfma_f32_16x16x32_bf16 v[34:37], v[166:169], v[204:207], v[34:37]
	v_mfma_f32_16x16x32_bf16 v[22:25], v[158:161], v[212:215], v[22:25]
	v_mfma_f32_16x16x32_bf16 v[18:21], v[166:169], v[212:215], v[18:21]
	v_mfma_f32_16x16x32_bf16 v[6:9], v[158:161], v[220:223], v[6:9]
	v_mfma_f32_16x16x32_bf16 v[2:5], v[166:169], v[220:223], v[2:5]
	s_setprio 0
	s_barrier
	s_add_i32 s42, s83, 2
	s_add_u32 s40, s40, 0x100
	s_addc_u32 s41, s41, 0
	s_cmp_gt_u32 s83, 13
	s_mov_b32 s83, s42
	s_cbranch_scc1 .LBB0_989

; #define PG8_STAGE(bufoff, gbase, voff) do { _Pragma("unroll") for (int _i = 0; _i < 2; ++_i) \
;         __builtin_amdgcn_global_load_lds((const unsigned*)((const char*)(gbase) + (voff)[_i]), (PG8_LAS unsigned*)(lds + (bufoff) + ldsw + _i * 8192), 16, 0, 0); } while (0)
; #define PG8_LDA(dst, b, h) do { _Pragma("unroll") for (int m = 0; m < 4; ++m) _Pragma("unroll") for (int k = 0; k < 2; ++k) dst[m][k] = *(const PG8_LAS bf16x8*)(lds + PG8_SA(b, h) + aoff + m * 2048 + k * 1024); } while (0)
; #define PG8_LDB(dst, b, h) do { _Pragma("unroll") for (int n = 0; n < 2; ++n) _Pragma("unroll") for (int k = 0; k < 2; ++k) dst[n][k] = *(const PG8_LAS bf16x8*)(lds + PG8_SB(b, h) + boff + n * 2048 + k * 1024); } while (0)
; #define PG8_MMA(ai, bj, At, Bt) do { __builtin_amdgcn_s_setprio(1); _Pragma("unroll") for (int m = 0; m < 4; ++m) _Pragma("unroll") for (int n = 0; n < 2; ++n) _Pragma("unroll") for (int k = 0; k < 2; ++k) \
;         acc[ai][bj][m][n] = __builtin_amdgcn_mfma_f32_16x16x32_bf16(Bt[n][k], At[m][k], acc[ai][bj][m][n], 0, 0, 0); __builtin_amdgcn_s_setprio(0); } while (0)
; #define PG8_WAIT_V(n) asm volatile("s_waitcnt vmcnt(" #n ")" ::: "memory")
; #define PG8_WAIT_L(n) asm volatile("s_waitcnt lgkmcnt(" #n ")" ::: "memory")
; #define PG8_BAR __builtin_amdgcn_s_barrier()
; template <class Epi, class Sched, bool ALIGN_EPI = false, bool SP2 = false>
; __device__ __forceinline__ void gemm_phase(PG8_LAS unsigned char* lds, const Gemm g, const Sched& S, const Epi& E) {
;     ...
;             PG8_LDB(B0, 0, 0); PG8_LDB(B1, 0, 1); PG8_SCHED; PG8_LDA(At, 0, 0); PG8_STAGE(PG8_SA(1, 1), a1 + hstep, voffA);
;             PG8_WAIT_V(8); PG8_WAIT_L(0); PG8_BAR; PG8_MMA(0, 0, At, B0); PG8_MMA(0, 1, At, B1); PG8_BAR; PG8_SCHED;
;             if constexpr (Epi::PREFETCH) { if (t == tpf) E.prefetch(cur, wid, lane); }
;             PG8_LDA(At, 0, 1); PG8_STAGE(PG8_SB(0, 0), b2, voffB); PG8_STAGE(PG8_SB(0, 1), b2 + hstep, voffB); PG8_STAGE(PG8_SA(0, 0), a2, voffA);
;             PG8_WAIT_V(8); PG8_WAIT_L(0); PG8_BAR; PG8_MMA(1, 0, At, B0); PG8_MMA(1, 1, At, B1); PG8_BAR; PG8_SCHED;
;     ...
;         for (int a = 0; a < 2; ++a)
; #pragma unroll
;             for (int b = 0; b < 2; ++b)
; #pragma unroll
;                 for (int m = 0; m < 4; ++m)
; #pragma unroll
;                     for (int n = 0; n < 2; ++n) acc[a][b][m][n] = (f32x4){0.f, 0.f, 0.f, 0.f};
.LBB0_1068:
	s_add_u32 s35, s6, 0x100
	s_addc_u32 s36, s7, 0
	s_mov_b32 s37, -2
	s_waitcnt lgkmcnt(0)
	ds_read_b128 v[130:133], v192
	ds_read_b128 v[134:137], v192 offset:1024
	ds_read_b128 v[156:159], v192 offset:2048
	ds_read_b128 v[160:163], v192 offset:3072
	ds_read_b128 v[164:167], v193
	ds_read_b128 v[168:171], v193 offset:1024
	ds_read_b128 v[172:175], v193 offset:2048
	ds_read_b128 v[176:179], v193 offset:3072
	s_add_u32 s0, s4, 0x200
	s_addc_u32 s1, s5, 0
	s_cmp_eq_u32 s37, 40
	s_cselect_b32 s31, s27, s1
	s_cselect_b32 s30, s26, s0
	s_cselect_b32 s7, s29, s36
	s_cselect_b32 s6, s28, s35
	v_lshl_add_u64 v[188:189], s[4:5], 0, v[148:149]
	s_add_i32 m0, s45, 0xc000
	ds_read_b128 v[180:183], v194
	ds_read_b128 v[184:187], v194 offset:1024
	ds_read_b128 v[196:199], v194 offset:2048
	ds_read_b128 v[200:203], v194 offset:3072
	ds_read_b128 v[204:207], v194 offset:4096
	ds_read_b128 v[208:211], v194 offset:5120
	ds_read_b128 v[212:215], v194 offset:6144
	ds_read_b128 v[216:219], v194 offset:7168
	global_load_lds_dwordx4 v[188:189], off
	v_lshl_add_u64 v[188:189], s[4:5], 0, v[150:151]
	s_add_i32 m0, s45, 0xe000
	s_nop 0
	global_load_lds_dwordx4 v[188:189], off
	s_waitcnt vmcnt(8)
	s_waitcnt lgkmcnt(0)
	s_barrier
	s_setprio 1
	s_waitcnt lgkmcnt(0)
	v_mfma_f32_16x16x32_bf16 v[126:129], v[130:133], v[180:183], 0
	v_mfma_f32_16x16x32_bf16 v[122:125], v[156:159], v[180:183], 0
	v_mfma_f32_16x16x32_bf16 v[110:113], v[130:133], v[196:199], 0
	v_mfma_f32_16x16x32_bf16 v[106:109], v[156:159], v[196:199], 0
	v_mfma_f32_16x16x32_bf16 v[94:97], v[130:133], v[204:207], 0
	v_mfma_f32_16x16x32_bf16 v[90:93], v[156:159], v[204:207], 0
	v_mfma_f32_16x16x32_bf16 v[78:81], v[130:133], v[212:215], 0
	v_mfma_f32_16x16x32_bf16 v[74:77], v[156:159], v[212:215], 0
	v_mfma_f32_16x16x32_bf16 v[126:129], v[134:137], v[184:187], v[126:129]
	v_mfma_f32_16x16x32_bf16 v[122:125], v[160:163], v[184:187], v[122:125]
	v_mfma_f32_16x16x32_bf16 v[110:113], v[134:137], v[200:203], v[110:113]
	v_mfma_f32_16x16x32_bf16 v[106:109], v[160:163], v[200:203], v[106:109]
	v_mfma_f32_16x16x32_bf16 v[94:97], v[134:137], v[208:211], v[94:97]
	v_mfma_f32_16x16x32_bf16 v[90:93], v[160:163], v[208:211], v[90:93]
	v_mfma_f32_16x16x32_bf16 v[78:81], v[134:137], v[216:219], v[78:81]
	v_mfma_f32_16x16x32_bf16 v[74:77], v[160:163], v[216:219], v[74:77]
	s_setprio 0
	s_setprio 1
	v_mfma_f32_16x16x32_bf16 v[118:121], v[164:167], v[180:183], 0
	v_mfma_f32_16x16x32_bf16 v[114:117], v[172:175], v[180:183], 0
	v_mfma_f32_16x16x32_bf16 v[102:105], v[164:167], v[196:199], 0
	v_mfma_f32_16x16x32_bf16 v[98:101], v[172:175], v[196:199], 0
	v_mfma_f32_16x16x32_bf16 v[86:89], v[164:167], v[204:207], 0
	v_mfma_f32_16x16x32_bf16 v[82:85], v[172:175], v[204:207], 0
	v_mfma_f32_16x16x32_bf16 v[70:73], v[164:167], v[212:215], 0
	v_mfma_f32_16x16x32_bf16 v[66:69], v[172:175], v[212:215], 0
	v_mfma_f32_16x16x32_bf16 v[118:121], v[168:171], v[184:187], v[118:121]
	v_mfma_f32_16x16x32_bf16 v[114:117], v[176:179], v[184:187], v[114:117]
	v_mfma_f32_16x16x32_bf16 v[102:105], v[168:171], v[200:203], v[102:105]
	v_mfma_f32_16x16x32_bf16 v[98:101], v[176:179], v[200:203], v[98:101]
	v_mfma_f32_16x16x32_bf16 v[86:89], v[168:171], v[208:211], v[86:89]
	v_mfma_f32_16x16x32_bf16 v[82:85], v[176:179], v[208:211], v[82:85]
	v_mfma_f32_16x16x32_bf16 v[70:73], v[168:171], v[216:219], v[70:73]
	v_mfma_f32_16x16x32_bf16 v[66:69], v[176:179], v[216:219], v[66:69]
	s_setprio 0
	s_barrier
	s_add_i32 s4, s61, s44
	v_lshl_add_u64 v[188:189], s[6:7], 0, v[140:141]
	s_mov_b32 m0, s4
	ds_read_b128 v[180:183], v194 offset:16384
	ds_read_b128 v[184:187], v194 offset:17408
	ds_read_b128 v[196:199], v194 offset:18432
	ds_read_b128 v[200:203], v194 offset:19456
	ds_read_b128 v[204:207], v194 offset:20480
	ds_read_b128 v[208:211], v194 offset:21504
	ds_read_b128 v[212:215], v194 offset:22528
	ds_read_b128 v[216:219], v194 offset:23552
	global_load_lds_dwordx4 v[188:189], off
	s_add_i32 m0, s4, 0x2000
	s_add_u32 s4, s6, 0xb0000
	v_lshl_add_u64 v[220:221], s[6:7], 0, v[144:145]
	s_addc_u32 s5, s7, 0
	s_add_i32 s38, s62, s44
	global_load_lds_dwordx4 v[220:221], off
	v_lshl_add_u64 v[222:223], s[4:5], 0, v[140:141]
	s_mov_b32 m0, s38
	v_lshl_add_u64 v[224:225], s[30:31], 0, v[142:143]
	global_load_lds_dwordx4 v[222:223], off
	v_lshl_add_u64 v[222:223], s[4:5], 0, v[144:145]
	s_add_i32 m0, s38, 0x2000
	s_nop 0
	global_load_lds_dwordx4 v[222:223], off
	v_lshl_add_u64 v[222:223], s[30:31], 0, v[138:139]
	s_mov_b32 m0, s45
	s_nop 0
	global_load_lds_dwordx4 v[222:223], off
	s_mov_b32 m0, s46
	s_nop 0
	global_load_lds_dwordx4 v[224:225], off
	s_waitcnt vmcnt(8)
	s_waitcnt lgkmcnt(0)
	s_barrier
	s_setprio 1
	s_waitcnt lgkmcnt(0)
	v_mfma_f32_16x16x32_bf16 v[62:65], v[130:133], v[180:183], 0
	v_mfma_f32_16x16x32_bf16 v[58:61], v[156:159], v[180:183], 0
	v_mfma_f32_16x16x32_bf16 v[46:49], v[130:133], v[196:199], 0
	v_mfma_f32_16x16x32_bf16 v[42:45], v[156:159], v[196:199], 0
	v_mfma_f32_16x16x32_bf16 v[30:33], v[130:133], v[204:207], 0
	v_mfma_f32_16x16x32_bf16 v[26:29], v[156:159], v[204:207], 0
	v_mfma_f32_16x16x32_bf16 v[14:17], v[130:133], v[212:215], 0
	v_mfma_f32_16x16x32_bf16 v[10:13], v[156:159], v[212:215], 0
	v_mfma_f32_16x16x32_bf16 v[62:65], v[134:137], v[184:187], v[62:65]
	v_mfma_f32_16x16x32_bf16 v[58:61], v[160:163], v[184:187], v[58:61]
	v_mfma_f32_16x16x32_bf16 v[46:49], v[134:137], v[200:203], v[46:49]
	v_mfma_f32_16x16x32_bf16 v[42:45], v[160:163], v[200:203], v[42:45]
	v_mfma_f32_16x16x32_bf16 v[30:33], v[134:137], v[208:211], v[30:33]
	v_mfma_f32_16x16x32_bf16 v[26:29], v[160:163], v[208:211], v[26:29]
	v_mfma_f32_16x16x32_bf16 v[14:17], v[134:137], v[216:219], v[14:17]
	v_mfma_f32_16x16x32_bf16 v[10:13], v[160:163], v[216:219], v[10:13]
	s_setprio 0
	s_setprio 1
	v_mfma_f32_16x16x32_bf16 v[54:57], v[164:167], v[180:183], 0
	v_mfma_f32_16x16x32_bf16 v[50:53], v[172:175], v[180:183], 0
	v_mfma_f32_16x16x32_bf16 v[38:41], v[164:167], v[196:199], 0
	v_mfma_f32_16x16x32_bf16 v[34:37], v[172:175], v[196:199], 0
	v_mfma_f32_16x16x32_bf16 v[22:25], v[164:167], v[204:207], 0
	v_mfma_f32_16x16x32_bf16 v[18:21], v[172:175], v[204:207], 0
	v_mfma_f32_16x16x32_bf16 v[6:9], v[164:167], v[212:215], 0
	v_mfma_f32_16x16x32_bf16 v[2:5], v[172:175], v[212:215], 0
	v_mfma_f32_16x16x32_bf16 v[54:57], v[168:171], v[184:187], v[54:57]
	v_mfma_f32_16x16x32_bf16 v[50:53], v[176:179], v[184:187], v[50:53]
	v_mfma_f32_16x16x32_bf16 v[38:41], v[168:171], v[200:203], v[38:41]
	v_mfma_f32_16x16x32_bf16 v[34:37], v[176:179], v[200:203], v[34:37]
	v_mfma_f32_16x16x32_bf16 v[22:25], v[168:171], v[208:211], v[22:25]
	v_mfma_f32_16x16x32_bf16 v[18:21], v[176:179], v[208:211], v[18:21]
	v_mfma_f32_16x16x32_bf16 v[6:9], v[168:171], v[216:219], v[6:9]
	v_mfma_f32_16x16x32_bf16 v[2:5], v[176:179], v[216:219], v[2:5]
	s_setprio 0
	s_barrier
	s_branch .Lpz6_mid

; #define PG8_STAGE(bufoff, gbase, voff) do { _Pragma("unroll") for (int _i = 0; _i < 2; ++_i) \
;         __builtin_amdgcn_global_load_lds((const unsigned*)((const char*)(gbase) + (voff)[_i]), (PG8_LAS unsigned*)(lds + (bufoff) + ldsw + _i * 8192), 16, 0, 0); } while (0)
; #define PG8_LDA(dst, b, h) do { _Pragma("unroll") for (int m = 0; m < 4; ++m) _Pragma("unroll") for (int k = 0; k < 2; ++k) dst[m][k] = *(const PG8_LAS bf16x8*)(lds + PG8_SA(b, h) + aoff + m * 2048 + k * 1024); } while (0)
; #define PG8_LDB(dst, b, h) do { _Pragma("unroll") for (int n = 0; n < 2; ++n) _Pragma("unroll") for (int k = 0; k < 2; ++k) dst[n][k] = *(const PG8_LAS bf16x8*)(lds + PG8_SB(b, h) + boff + n * 2048 + k * 1024); } while (0)
; #define PG8_MMA(ai, bj, At, Bt) do { __builtin_amdgcn_s_setprio(1); _Pragma("unroll") for (int m = 0; m < 4; ++m) _Pragma("unroll") for (int n = 0; n < 2; ++n) _Pragma("unroll") for (int k = 0; k < 2; ++k) \
;         acc[ai][bj][m][n] = __builtin_amdgcn_mfma_f32_16x16x32_bf16(Bt[n][k], At[m][k], acc[ai][bj][m][n], 0, 0, 0); __builtin_amdgcn_s_setprio(0); } while (0)
; #define PG8_WAIT_V(n) asm volatile("s_waitcnt vmcnt(" #n ")" ::: "memory")
; #define PG8_WAIT_L(n) asm volatile("s_waitcnt lgkmcnt(" #n ")" ::: "memory")
; #define PG8_BAR __builtin_amdgcn_s_barrier()
; #define PG8_SCHED __builtin_amdgcn_sched_barrier(0)
; template <class Epi, class Sched, bool ALIGN_EPI = false, bool SP2 = false>
; __device__ __forceinline__ void gemm_phase(PG8_LAS unsigned char* lds, const Gemm g, const Sched& S, const Epi& E) {
;     ...
;             PG8_LDB(B0, 1, 0); PG8_LDB(B1, 1, 1); PG8_SCHED; PG8_LDA(At, 1, 0); PG8_STAGE(PG8_SA(0, 1), a2 + hstep, voffA);
;             PG8_WAIT_V(8); PG8_WAIT_L(0); PG8_BAR; PG8_MMA(0, 0, At, B0); PG8_MMA(0, 1, At, B1); PG8_BAR; PG8_SCHED;
.Lpz6_mid:
	s_add_i32 s38, 0, 0x18000
	v_add_u32_e32 v146, s38, v191
	s_add_i32 s39, 0, 0x1c000
	ds_read_b128 v[130:133], v146
	ds_read_b128 v[134:137], v146 offset:1024
	ds_read_b128 v[156:159], v146 offset:2048
	ds_read_b128 v[160:163], v146 offset:3072
	v_add_u32_e32 v146, s39, v191
	ds_read_b128 v[164:167], v146
	ds_read_b128 v[168:171], v146 offset:1024
	ds_read_b128 v[172:175], v146 offset:2048
	ds_read_b128 v[176:179], v146 offset:3072
	s_add_u32 s4, s30, 0xb0000
	s_addc_u32 s5, s31, 0
	s_mov_b32 m0, s47
	v_lshl_add_u64 v[226:227], s[4:5], 0, v[138:139]
	ds_read_b128 v[180:183], v194 offset:32768
	ds_read_b128 v[184:187], v194 offset:33792
	ds_read_b128 v[196:199], v194 offset:34816
	ds_read_b128 v[200:203], v194 offset:35840
	ds_read_b128 v[204:207], v194 offset:36864
	ds_read_b128 v[208:211], v194 offset:37888
	ds_read_b128 v[212:215], v194 offset:38912
	ds_read_b128 v[216:219], v194 offset:39936
	global_load_lds_dwordx4 v[226:227], off
	v_lshl_add_u64 v[226:227], s[4:5], 0, v[142:143]
	s_mov_b32 m0, s48
	s_nop 0
	global_load_lds_dwordx4 v[226:227], off
	s_waitcnt vmcnt(8)
	s_waitcnt lgkmcnt(0)
	s_barrier
	s_setprio 1
	s_waitcnt lgkmcnt(0)
	v_mfma_f32_16x16x32_bf16 v[126:129], v[130:133], v[180:183], v[126:129]
	v_mfma_f32_16x16x32_bf16 v[122:125], v[156:159], v[180:183], v[122:125]
	v_mfma_f32_16x16x32_bf16 v[110:113], v[130:133], v[196:199], v[110:113]
	v_mfma_f32_16x16x32_bf16 v[106:109], v[156:159], v[196:199], v[106:109]
	v_mfma_f32_16x16x32_bf16 v[94:97], v[130:133], v[204:207], v[94:97]
	v_mfma_f32_16x16x32_bf16 v[90:93], v[156:159], v[204:207], v[90:93]
	v_mfma_f32_16x16x32_bf16 v[78:81], v[130:133], v[212:215], v[78:81]
	v_mfma_f32_16x16x32_bf16 v[74:77], v[156:159], v[212:215], v[74:77]
	v_mfma_f32_16x16x32_bf16 v[126:129], v[134:137], v[184:187], v[126:129]
	v_mfma_f32_16x16x32_bf16 v[122:125], v[160:163], v[184:187], v[122:125]
	v_mfma_f32_16x16x32_bf16 v[110:113], v[134:137], v[200:203], v[110:113]
	v_mfma_f32_16x16x32_bf16 v[106:109], v[160:163], v[200:203], v[106:109]
	v_mfma_f32_16x16x32_bf16 v[94:97], v[134:137], v[208:211], v[94:97]
	v_mfma_f32_16x16x32_bf16 v[90:93], v[160:163], v[208:211], v[90:93]
	v_mfma_f32_16x16x32_bf16 v[78:81], v[134:137], v[216:219], v[78:81]
	v_mfma_f32_16x16x32_bf16 v[74:77], v[160:163], v[216:219], v[74:77]
	s_setprio 0
	s_setprio 1
	v_mfma_f32_16x16x32_bf16 v[118:121], v[164:167], v[180:183], v[118:121]
	v_mfma_f32_16x16x32_bf16 v[114:117], v[172:175], v[180:183], v[114:117]
	v_mfma_f32_16x16x32_bf16 v[102:105], v[164:167], v[196:199], v[102:105]
	v_mfma_f32_16x16x32_bf16 v[98:101], v[172:175], v[196:199], v[98:101]
	v_mfma_f32_16x16x32_bf16 v[86:89], v[164:167], v[204:207], v[86:89]
	v_mfma_f32_16x16x32_bf16 v[82:85], v[172:175], v[204:207], v[82:85]
	v_mfma_f32_16x16x32_bf16 v[70:73], v[164:167], v[212:215], v[70:73]
	v_mfma_f32_16x16x32_bf16 v[66:69], v[172:175], v[212:215], v[66:69]
	v_mfma_f32_16x16x32_bf16 v[118:121], v[168:171], v[184:187], v[118:121]
	v_mfma_f32_16x16x32_bf16 v[114:117], v[176:179], v[184:187], v[114:117]
	v_mfma_f32_16x16x32_bf16 v[102:105], v[168:171], v[200:203], v[102:105]
	v_mfma_f32_16x16x32_bf16 v[98:101], v[176:179], v[200:203], v[98:101]
	v_mfma_f32_16x16x32_bf16 v[86:89], v[168:171], v[208:211], v[86:89]
	v_mfma_f32_16x16x32_bf16 v[82:85], v[176:179], v[208:211], v[82:85]
	v_mfma_f32_16x16x32_bf16 v[70:73], v[168:171], v[216:219], v[70:73]
	v_mfma_f32_16x16x32_bf16 v[66:69], v[176:179], v[216:219], v[66:69]
	s_setprio 0
	s_barrier
; #define PG8_STAGE(bufoff, gbase, voff) do { _Pragma("unroll") for (int _i = 0; _i < 2; ++_i) \
;         __builtin_amdgcn_global_load_lds((const unsigned*)((const char*)(gbase) + (voff)[_i]), (PG8_LAS unsigned*)(lds + (bufoff) + ldsw + _i * 8192), 16, 0, 0); } while (0)
; #define PG8_LDA(dst, b, h) do { _Pragma("unroll") for (int m = 0; m < 4; ++m) _Pragma("unroll") for (int k = 0; k < 2; ++k) dst[m][k] = *(const PG8_LAS bf16x8*)(lds + PG8_SA(b, h) + aoff + m * 2048 + k * 1024); } while (0)
; #define PG8_MMA(ai, bj, At, Bt) do { __builtin_amdgcn_s_setprio(1); _Pragma("unroll") for (int m = 0; m < 4; ++m) _Pragma("unroll") for (int n = 0; n < 2; ++n) _Pragma("unroll") for (int k = 0; k < 2; ++k) \
;         acc[ai][bj][m][n] = __builtin_amdgcn_mfma_f32_16x16x32_bf16(Bt[n][k], At[m][k], acc[ai][bj][m][n], 0, 0, 0); __builtin_amdgcn_s_setprio(0); } while (0)
; #define PG8_WAIT_V(n) asm volatile("s_waitcnt vmcnt(" #n ")" ::: "memory")
; #define PG8_WAIT_L(n) asm volatile("s_waitcnt lgkmcnt(" #n ")" ::: "memory")
; #define PG8_BAR __builtin_amdgcn_s_barrier()
; #define PG8_SCHED __builtin_amdgcn_sched_barrier(0)
; template <class Epi, class Sched, bool ALIGN_EPI = false, bool SP2 = false>
; __device__ __forceinline__ void gemm_phase(PG8_LAS unsigned char* lds, const Gemm g, const Sched& S, const Epi& E) {
;     ...
;             PG8_LDA(At, 1, 1); PG8_STAGE(PG8_SB(1, 0), b3, voffB); PG8_STAGE(PG8_SB(1, 1), b3 + hstep, voffB); PG8_STAGE(PG8_SA(1, 0), a3, voffA);
;             PG8_WAIT_V(8); PG8_WAIT_L(0); PG8_BAR; PG8_MMA(1, 0, At, B0); PG8_MMA(1, 1, At, B1); PG8_BAR; PG8_SCHED;
;     ...
;         }
;         if constexpr (ALIGN_EPI) { if (wr == 0) PG8_BAR; }
	s_add_i32 s4, s38, s44
	v_lshl_add_u64 v[188:189], v[188:189], 0, s[18:19]
	s_mov_b32 m0, s4
	ds_read_b128 v[180:183], v194 offset:49152
	ds_read_b128 v[184:187], v194 offset:50176
	ds_read_b128 v[196:199], v194 offset:51200
	ds_read_b128 v[200:203], v194 offset:52224
	ds_read_b128 v[204:207], v194 offset:53248
	ds_read_b128 v[208:211], v194 offset:54272
	ds_read_b128 v[212:215], v194 offset:55296
	ds_read_b128 v[216:219], v194 offset:56320
	global_load_lds_dwordx4 v[188:189], off
	s_add_i32 m0, s4, 0x2000
	s_add_u32 s4, s6, 0xb0080
	v_lshl_add_u64 v[188:189], v[220:221], 0, s[18:19]
	s_addc_u32 s5, s7, 0
	s_add_i32 s6, s39, s44
	global_load_lds_dwordx4 v[188:189], off
	v_lshl_add_u64 v[188:189], s[4:5], 0, v[140:141]
	s_mov_b32 m0, s6
	s_nop 0
	global_load_lds_dwordx4 v[188:189], off
	v_lshl_add_u64 v[188:189], s[4:5], 0, v[144:145]
	s_add_i32 m0, s6, 0x2000
	s_nop 0
	global_load_lds_dwordx4 v[188:189], off
	v_lshl_add_u64 v[188:189], v[222:223], 0, s[20:21]
	s_mov_b32 m0, s55
	s_nop 0
	global_load_lds_dwordx4 v[188:189], off
	v_lshl_add_u64 v[188:189], v[224:225], 0, s[20:21]
	s_mov_b32 m0, s56
	s_nop 0
	global_load_lds_dwordx4 v[188:189], off
	s_waitcnt vmcnt(8)
	s_waitcnt lgkmcnt(0)
	s_barrier
	s_setprio 1
	s_waitcnt lgkmcnt(0)
	v_mfma_f32_16x16x32_bf16 v[62:65], v[130:133], v[180:183], v[62:65]
	v_mfma_f32_16x16x32_bf16 v[58:61], v[156:159], v[180:183], v[58:61]
	v_mfma_f32_16x16x32_bf16 v[46:49], v[130:133], v[196:199], v[46:49]
	v_mfma_f32_16x16x32_bf16 v[42:45], v[156:159], v[196:199], v[42:45]
	v_mfma_f32_16x16x32_bf16 v[30:33], v[130:133], v[204:207], v[30:33]
	v_mfma_f32_16x16x32_bf16 v[26:29], v[156:159], v[204:207], v[26:29]
	v_mfma_f32_16x16x32_bf16 v[14:17], v[130:133], v[212:215], v[14:17]
	v_mfma_f32_16x16x32_bf16 v[10:13], v[156:159], v[212:215], v[10:13]
	v_mfma_f32_16x16x32_bf16 v[62:65], v[134:137], v[184:187], v[62:65]
	v_mfma_f32_16x16x32_bf16 v[58:61], v[160:163], v[184:187], v[58:61]
	v_mfma_f32_16x16x32_bf16 v[46:49], v[134:137], v[200:203], v[46:49]
	v_mfma_f32_16x16x32_bf16 v[42:45], v[160:163], v[200:203], v[42:45]
	v_mfma_f32_16x16x32_bf16 v[30:33], v[134:137], v[208:211], v[30:33]
	v_mfma_f32_16x16x32_bf16 v[26:29], v[160:163], v[208:211], v[26:29]
	v_mfma_f32_16x16x32_bf16 v[14:17], v[134:137], v[216:219], v[14:17]
	v_mfma_f32_16x16x32_bf16 v[10:13], v[160:163], v[216:219], v[10:13]
	s_setprio 0
	s_setprio 1
	v_mfma_f32_16x16x32_bf16 v[54:57], v[164:167], v[180:183], v[54:57]
	v_mfma_f32_16x16x32_bf16 v[50:53], v[172:175], v[180:183], v[50:53]
	v_mfma_f32_16x16x32_bf16 v[38:41], v[164:167], v[196:199], v[38:41]
	v_mfma_f32_16x16x32_bf16 v[34:37], v[172:175], v[196:199], v[34:37]
	v_mfma_f32_16x16x32_bf16 v[22:25], v[164:167], v[204:207], v[22:25]
	v_mfma_f32_16x16x32_bf16 v[18:21], v[172:175], v[204:207], v[18:21]
	v_mfma_f32_16x16x32_bf16 v[6:9], v[164:167], v[212:215], v[6:9]
	v_mfma_f32_16x16x32_bf16 v[2:5], v[172:175], v[212:215], v[2:5]
	v_mfma_f32_16x16x32_bf16 v[54:57], v[168:171], v[184:187], v[54:57]
	v_mfma_f32_16x16x32_bf16 v[50:53], v[176:179], v[184:187], v[50:53]
	v_mfma_f32_16x16x32_bf16 v[38:41], v[168:171], v[200:203], v[38:41]
	v_mfma_f32_16x16x32_bf16 v[34:37], v[176:179], v[200:203], v[34:37]
	v_mfma_f32_16x16x32_bf16 v[22:25], v[168:171], v[208:211], v[22:25]
	v_mfma_f32_16x16x32_bf16 v[18:21], v[176:179], v[208:211], v[18:21]
	v_mfma_f32_16x16x32_bf16 v[6:9], v[168:171], v[216:219], v[6:9]
	v_mfma_f32_16x16x32_bf16 v[2:5], v[176:179], v[216:219], v[2:5]
	s_setprio 0
	s_barrier
	s_add_i32 s37, s37, 2
	s_add_u32 s35, s35, 0x100
	s_addc_u32 s36, s36, 0
	s_cmp_gt_u32 s37, 41
	s_mov_b64 s[4:5], s[0:1]
	s_cbranch_scc0 .LBB0_1069
	s_and_b64 vcc, exec, s[22:23]
	s_cbranch_vccz .LBB0_1072
	s_barrier
